# GEMM loops without s_setprio pair (memory ops now interleaved inside the compute segment)
# baseline (speedup 1.0000x reference)
; #define G_STORE(ST, S, unused) do { char* d_ = smem + (ST) * STAGE; \
;     *(uint4*)(d_ + alo[0]) = S##a0; *(uint4*)(d_ + alo[1]) = S##a1; *(uint4*)(d_ + alo[2]) = S##a2; *(uint4*)(d_ + alo[3]) = S##a3; \
;     *(uint4*)(d_ + blo[0]) = S##b0; *(uint4*)(d_ + blo[1]) = S##b1; \
;     if (NBCH == 4) { *(uint4*)(d_ + blo[NBCH - 2]) = S##b2; *(uint4*)(d_ + blo[NBCH - 1]) = S##b3; } } while (0)
; template <int NJ, class RowA>
; DI void gemm_main(f32x16 (&acc)[2][NJ], const bf16_t* __restrict__ A, RowA rowA, size_t kstrideA, int m0, int Mmax,
;                   const bf16_t* __restrict__ Bt, size_t ldb, int n0, int nk, char* smem) {
;     ...
;   __syncthreads();
;   G_LOAD(x0, 0, 0);
;   G_LOAD(x1, 0, 1);
;   G_STORE(0, x0, 0);
;   __syncthreads();
; #pragma unroll 1
;   for (int kt = 0; kt < nk; kt += 2) {
;     G_LOAD(x0, 0, (kt + 2 < nk ? kt + 2 : nk - 1));
;     G_COMPUTE(0);
;     G_STORE(1, x1, 0);
;     __syncthreads();
;     G_LOAD(x1, 0, (kt + 3 < nk ? kt + 3 : nk - 1));
;     G_COMPUTE(1);
;     G_STORE(0, x0, 0);
;     __syncthreads();
.LBB0_12:
	s_cmp_lt_i32 s3, 12
	s_cbranch_scc0 .Lpeel_tail_12
	ds_read_b128 v[166:169], v0
	ds_read_b128 v[170:173], v139 offset:18432
	ds_read_b128 v[174:177], v139 offset:23040
	ds_read_b128 v[178:181], v0 offset:4608
	s_add_i32 s4, s3, 4
	s_min_u32 s4, s4, 15
	s_lshl_b32 s14, s4, 7
	v_lshl_add_u64 v[98:99], v[122:123], 0, s[14:15]
	v_lshl_add_u64 v[102:103], v[124:125], 0, s[14:15]
	v_lshl_add_u64 v[106:107], v[126:127], 0, s[14:15]
	v_lshl_add_u64 v[110:111], v[128:129], 0, s[14:15]
	v_lshl_add_u64 v[114:115], v[130:131], 0, s[14:15]
	v_lshl_add_u64 v[118:119], v[132:133], 0, s[14:15]
	s_add_i32 s3, s3, 2
	v_lshl_add_u64 v[158:159], v[134:135], 0, s[14:15]
	v_lshl_add_u64 v[160:161], v[136:137], 0, s[14:15]
	ds_read_b128 v[182:185], v0 offset:32
	ds_read_b128 v[186:189], v139 offset:18464
	ds_read_b128 v[190:193], v139 offset:23072
	ds_read_b128 v[194:197], v0 offset:4640
	s_waitcnt lgkmcnt(4)
	v_mfma_f32_32x32x16_bf16 v[50:65], v[166:169], v[170:173], v[50:65]
	global_load_dwordx4 v[98:101], v[98:99], off
	v_mfma_f32_32x32x16_bf16 v[34:49], v[166:169], v[174:177], v[34:49]
	global_load_dwordx4 v[102:105], v[102:103], off
	v_mfma_f32_32x32x16_bf16 v[18:33], v[178:181], v[170:173], v[18:33]
	global_load_dwordx4 v[106:109], v[106:107], off
	v_mfma_f32_32x32x16_bf16 v[2:17], v[178:181], v[174:177], v[2:17]
	global_load_dwordx4 v[110:113], v[110:111], off
	ds_read_b128 v[166:169], v0 offset:64
	ds_read_b128 v[170:173], v139 offset:18496
	ds_read_b128 v[174:177], v139 offset:23104
	ds_read_b128 v[178:181], v0 offset:4672
	s_waitcnt lgkmcnt(4)
	v_mfma_f32_32x32x16_bf16 v[50:65], v[182:185], v[186:189], v[50:65]
	global_load_dwordx4 v[114:117], v[114:115], off
	v_mfma_f32_32x32x16_bf16 v[34:49], v[182:185], v[190:193], v[34:49]
	global_load_dwordx4 v[118:121], v[118:119], off
	v_mfma_f32_32x32x16_bf16 v[18:33], v[194:197], v[186:189], v[18:33]
	global_load_dwordx4 v[146:149], v[160:161], off
	v_mfma_f32_32x32x16_bf16 v[2:17], v[194:197], v[190:193], v[2:17]
	global_load_dwordx4 v[150:153], v[158:159], off
	ds_read_b128 v[182:185], v0 offset:96
	ds_read_b128 v[186:189], v139 offset:18528
	ds_read_b128 v[190:193], v139 offset:23136
	ds_read_b128 v[194:197], v0 offset:4704
	s_waitcnt lgkmcnt(4)
	v_mfma_f32_32x32x16_bf16 v[50:65], v[166:169], v[170:173], v[50:65]
	s_waitcnt vmcnt(8)
	ds_write_b128 v138, v[78:81] offset:36864
	v_mfma_f32_32x32x16_bf16 v[34:49], v[166:169], v[174:177], v[34:49]
	ds_write_b128 v140, v[86:89] offset:36864
	v_mfma_f32_32x32x16_bf16 v[18:33], v[178:181], v[170:173], v[18:33]
	ds_write_b128 v142, v[90:93] offset:36864
	v_mfma_f32_32x32x16_bf16 v[2:17], v[178:181], v[174:177], v[2:17]
	ds_write_b128 v144, v[94:97] offset:36864
	s_waitcnt lgkmcnt(4)
	v_mfma_f32_32x32x16_bf16 v[50:65], v[182:185], v[186:189], v[50:65]
	ds_write_b128 v138, v[74:77] offset:55296
	v_mfma_f32_32x32x16_bf16 v[34:49], v[182:185], v[190:193], v[34:49]
	ds_write_b128 v140, v[82:85] offset:55296
	v_mfma_f32_32x32x16_bf16 v[18:33], v[194:197], v[186:189], v[18:33]
	ds_write_b128 v142, v[66:69] offset:55296
	v_mfma_f32_32x32x16_bf16 v[2:17], v[194:197], v[190:193], v[2:17]
	ds_write_b128 v144, v[70:73] offset:55296
	s_min_u32 s4, s3, 12
	s_lshl_b32 s14, s4, 7
	v_lshl_add_u64 v[66:67], v[122:123], 0, s[14:15]
	v_lshl_add_u64 v[68:69], v[124:125], 0, s[14:15]
	v_lshl_add_u64 v[70:71], v[126:127], 0, s[14:15]
	v_lshl_add_u64 v[72:73], v[128:129], 0, s[14:15]
	v_lshl_add_u64 v[74:75], v[130:131], 0, s[14:15]
	v_lshl_add_u64 v[82:83], v[132:133], 0, s[14:15]
	s_waitcnt lgkmcnt(0)
	s_barrier
	ds_read_b128 v[166:169], v0 offset:36864
	ds_read_b128 v[170:173], v139 offset:55296
	ds_read_b128 v[174:177], v139 offset:59904
	ds_read_b128 v[178:181], v0 offset:41472
	v_lshl_add_u64 v[154:155], v[134:135], 0, s[14:15]
	v_lshl_add_u64 v[156:157], v[136:137], 0, s[14:15]
	ds_read_b128 v[182:185], v0 offset:36896
	ds_read_b128 v[186:189], v139 offset:55328
	ds_read_b128 v[190:193], v139 offset:59936
	ds_read_b128 v[194:197], v0 offset:41504
	s_waitcnt lgkmcnt(4)
	v_mfma_f32_32x32x16_bf16 v[50:65], v[166:169], v[170:173], v[50:65]
	global_load_dwordx4 v[78:81], v[66:67], off offset:384
	v_mfma_f32_32x32x16_bf16 v[34:49], v[166:169], v[174:177], v[34:49]
	global_load_dwordx4 v[86:89], v[68:69], off offset:384
	v_mfma_f32_32x32x16_bf16 v[18:33], v[178:181], v[170:173], v[18:33]
	global_load_dwordx4 v[90:93], v[70:71], off offset:384
	v_mfma_f32_32x32x16_bf16 v[2:17], v[178:181], v[174:177], v[2:17]
	global_load_dwordx4 v[94:97], v[72:73], off offset:384
	ds_read_b128 v[166:169], v0 offset:36928
	ds_read_b128 v[170:173], v139 offset:55360
	ds_read_b128 v[174:177], v139 offset:59968
	ds_read_b128 v[178:181], v0 offset:41536
	s_waitcnt lgkmcnt(4)
	v_mfma_f32_32x32x16_bf16 v[50:65], v[182:185], v[186:189], v[50:65]
	global_load_dwordx4 v[74:77], v[74:75], off offset:384
	v_mfma_f32_32x32x16_bf16 v[34:49], v[182:185], v[190:193], v[34:49]
	global_load_dwordx4 v[82:85], v[82:83], off offset:384
	v_mfma_f32_32x32x16_bf16 v[18:33], v[194:197], v[186:189], v[18:33]
	global_load_dwordx4 v[66:69], v[154:155], off offset:384
	v_mfma_f32_32x32x16_bf16 v[2:17], v[194:197], v[190:193], v[2:17]
	global_load_dwordx4 v[70:73], v[156:157], off offset:384
	ds_read_b128 v[182:185], v0 offset:36960
	ds_read_b128 v[186:189], v139 offset:55392
	ds_read_b128 v[190:193], v139 offset:60000
	ds_read_b128 v[194:197], v0 offset:41568
	s_waitcnt lgkmcnt(4)
	v_mfma_f32_32x32x16_bf16 v[50:65], v[166:169], v[170:173], v[50:65]
	s_waitcnt vmcnt(8)
	ds_write_b128 v138, v[98:101]
	v_mfma_f32_32x32x16_bf16 v[34:49], v[166:169], v[174:177], v[34:49]
	ds_write_b128 v140, v[102:105]
	v_mfma_f32_32x32x16_bf16 v[18:33], v[178:181], v[170:173], v[18:33]
	ds_write_b128 v142, v[106:109]
	v_mfma_f32_32x32x16_bf16 v[2:17], v[178:181], v[174:177], v[2:17]
	ds_write_b128 v144, v[110:113]
	s_waitcnt lgkmcnt(4)
	v_mfma_f32_32x32x16_bf16 v[50:65], v[182:185], v[186:189], v[50:65]
	ds_write_b128 v138, v[114:117] offset:18432
	v_mfma_f32_32x32x16_bf16 v[34:49], v[182:185], v[190:193], v[34:49]
	ds_write_b128 v140, v[118:121] offset:18432
	v_mfma_f32_32x32x16_bf16 v[18:33], v[194:197], v[186:189], v[18:33]
	ds_write_b128 v142, v[150:153] offset:18432
	v_mfma_f32_32x32x16_bf16 v[2:17], v[194:197], v[190:193], v[2:17]
	ds_write_b128 v144, v[146:149] offset:18432
	s_cmp_lt_u32 s3, 14
	s_waitcnt lgkmcnt(0)
	s_barrier
	s_branch .LBB0_12
; #define G_STORE(ST, S, unused) do { char* d_ = smem + (ST) * STAGE; \
;     *(uint4*)(d_ + alo[0]) = S##a0; *(uint4*)(d_ + alo[1]) = S##a1; *(uint4*)(d_ + alo[2]) = S##a2; *(uint4*)(d_ + alo[3]) = S##a3; \
;     *(uint4*)(d_ + blo[0]) = S##b0; *(uint4*)(d_ + blo[1]) = S##b1; \
;     if (NBCH == 4) { *(uint4*)(d_ + blo[NBCH - 2]) = S##b2; *(uint4*)(d_ + blo[NBCH - 1]) = S##b3; } } while (0)
; template <int NJ, class RowA>
; DI void gemm_main(f32x16 (&acc)[2][NJ], const bf16_t* __restrict__ A, RowA rowA, size_t kstrideA, int m0, int Mmax,
;                   const bf16_t* __restrict__ Bt, size_t ldb, int n0, int nk, char* smem) {
;     ...
;   __syncthreads();
;   G_LOAD(x0, 0, 0);
;   G_LOAD(x1, 0, 1);
;   G_STORE(0, x0, 0);
;   __syncthreads();
; #pragma unroll 1
;   for (int kt = 0; kt < nk; kt += 2) {
;     G_LOAD(x0, 0, (kt + 2 < nk ? kt + 2 : nk - 1));
;     G_COMPUTE(0);
;     G_STORE(1, x1, 0);
;     __syncthreads();
;     G_LOAD(x1, 0, (kt + 3 < nk ? kt + 3 : nk - 1));
;     G_COMPUTE(1);
;     G_STORE(0, x0, 0);
;     __syncthreads();
.Lpeel_tail_12:
	ds_read_b128 v[166:169], v0
	ds_read_b128 v[170:173], v139 offset:18432
	ds_read_b128 v[174:177], v139 offset:23040
	ds_read_b128 v[178:181], v0 offset:4608
	s_add_i32 s4, s3, 4
	s_min_u32 s4, s4, 15
	s_lshl_b32 s14, s4, 7
	v_lshl_add_u64 v[98:99], v[122:123], 0, s[14:15]
	v_lshl_add_u64 v[102:103], v[124:125], 0, s[14:15]
	v_lshl_add_u64 v[106:107], v[126:127], 0, s[14:15]
	v_lshl_add_u64 v[110:111], v[128:129], 0, s[14:15]
	v_lshl_add_u64 v[114:115], v[130:131], 0, s[14:15]
	v_lshl_add_u64 v[118:119], v[132:133], 0, s[14:15]
	s_add_i32 s3, s3, 2
	v_lshl_add_u64 v[158:159], v[134:135], 0, s[14:15]
	v_lshl_add_u64 v[160:161], v[136:137], 0, s[14:15]
	ds_read_b128 v[182:185], v0 offset:32
	ds_read_b128 v[186:189], v139 offset:18464
	ds_read_b128 v[190:193], v139 offset:23072
	ds_read_b128 v[194:197], v0 offset:4640
	s_waitcnt lgkmcnt(4)
	v_mfma_f32_32x32x16_bf16 v[50:65], v[166:169], v[170:173], v[50:65]
	v_mfma_f32_32x32x16_bf16 v[34:49], v[166:169], v[174:177], v[34:49]
	v_mfma_f32_32x32x16_bf16 v[18:33], v[178:181], v[170:173], v[18:33]
	v_mfma_f32_32x32x16_bf16 v[2:17], v[178:181], v[174:177], v[2:17]
	ds_read_b128 v[166:169], v0 offset:64
	ds_read_b128 v[170:173], v139 offset:18496
	ds_read_b128 v[174:177], v139 offset:23104
	ds_read_b128 v[178:181], v0 offset:4672
	s_waitcnt lgkmcnt(4)
	v_mfma_f32_32x32x16_bf16 v[50:65], v[182:185], v[186:189], v[50:65]
	v_mfma_f32_32x32x16_bf16 v[34:49], v[182:185], v[190:193], v[34:49]
	v_mfma_f32_32x32x16_bf16 v[18:33], v[194:197], v[186:189], v[18:33]
	v_mfma_f32_32x32x16_bf16 v[2:17], v[194:197], v[190:193], v[2:17]
	ds_read_b128 v[182:185], v0 offset:96
	ds_read_b128 v[186:189], v139 offset:18528
	ds_read_b128 v[190:193], v139 offset:23136
	ds_read_b128 v[194:197], v0 offset:4704
	s_waitcnt lgkmcnt(4)
	v_mfma_f32_32x32x16_bf16 v[50:65], v[166:169], v[170:173], v[50:65]
	s_waitcnt vmcnt(0)
	ds_write_b128 v138, v[78:81] offset:36864
	v_mfma_f32_32x32x16_bf16 v[34:49], v[166:169], v[174:177], v[34:49]
	ds_write_b128 v140, v[86:89] offset:36864
	v_mfma_f32_32x32x16_bf16 v[18:33], v[178:181], v[170:173], v[18:33]
	ds_write_b128 v142, v[90:93] offset:36864
	v_mfma_f32_32x32x16_bf16 v[2:17], v[178:181], v[174:177], v[2:17]
	ds_write_b128 v144, v[94:97] offset:36864
	s_waitcnt lgkmcnt(4)
	v_mfma_f32_32x32x16_bf16 v[50:65], v[182:185], v[186:189], v[50:65]
	ds_write_b128 v138, v[74:77] offset:55296
	v_mfma_f32_32x32x16_bf16 v[34:49], v[182:185], v[190:193], v[34:49]
	ds_write_b128 v140, v[82:85] offset:55296
	v_mfma_f32_32x32x16_bf16 v[18:33], v[194:197], v[186:189], v[18:33]
	ds_write_b128 v142, v[66:69] offset:55296
	v_mfma_f32_32x32x16_bf16 v[2:17], v[194:197], v[190:193], v[2:17]
	ds_write_b128 v144, v[70:73] offset:55296
	s_min_u32 s4, s3, 12
	s_lshl_b32 s14, s4, 7
	v_lshl_add_u64 v[66:67], v[122:123], 0, s[14:15]
	v_lshl_add_u64 v[68:69], v[124:125], 0, s[14:15]
	v_lshl_add_u64 v[70:71], v[126:127], 0, s[14:15]
	v_lshl_add_u64 v[72:73], v[128:129], 0, s[14:15]
	v_lshl_add_u64 v[74:75], v[130:131], 0, s[14:15]
	v_lshl_add_u64 v[82:83], v[132:133], 0, s[14:15]
	s_waitcnt lgkmcnt(0)
	s_barrier
	ds_read_b128 v[166:169], v0 offset:36864
	ds_read_b128 v[170:173], v139 offset:55296
	ds_read_b128 v[174:177], v139 offset:59904
	ds_read_b128 v[178:181], v0 offset:41472
	v_lshl_add_u64 v[154:155], v[134:135], 0, s[14:15]
	v_lshl_add_u64 v[156:157], v[136:137], 0, s[14:15]
	ds_read_b128 v[182:185], v0 offset:36896
	ds_read_b128 v[186:189], v139 offset:55328
	ds_read_b128 v[190:193], v139 offset:59936
	ds_read_b128 v[194:197], v0 offset:41504
	s_waitcnt lgkmcnt(4)
	v_mfma_f32_32x32x16_bf16 v[50:65], v[166:169], v[170:173], v[50:65]
	v_mfma_f32_32x32x16_bf16 v[34:49], v[166:169], v[174:177], v[34:49]
	v_mfma_f32_32x32x16_bf16 v[18:33], v[178:181], v[170:173], v[18:33]
	v_mfma_f32_32x32x16_bf16 v[2:17], v[178:181], v[174:177], v[2:17]
	ds_read_b128 v[166:169], v0 offset:36928
	ds_read_b128 v[170:173], v139 offset:55360
	ds_read_b128 v[174:177], v139 offset:59968
	ds_read_b128 v[178:181], v0 offset:41536
	s_waitcnt lgkmcnt(4)
	v_mfma_f32_32x32x16_bf16 v[50:65], v[182:185], v[186:189], v[50:65]
	v_mfma_f32_32x32x16_bf16 v[34:49], v[182:185], v[190:193], v[34:49]
	v_mfma_f32_32x32x16_bf16 v[18:33], v[194:197], v[186:189], v[18:33]
	v_mfma_f32_32x32x16_bf16 v[2:17], v[194:197], v[190:193], v[2:17]
	ds_read_b128 v[182:185], v0 offset:36960
	ds_read_b128 v[186:189], v139 offset:55392
	ds_read_b128 v[190:193], v139 offset:60000
	ds_read_b128 v[194:197], v0 offset:41568
	s_waitcnt lgkmcnt(4)
	v_mfma_f32_32x32x16_bf16 v[50:65], v[166:169], v[170:173], v[50:65]
	v_mfma_f32_32x32x16_bf16 v[34:49], v[166:169], v[174:177], v[34:49]
	v_mfma_f32_32x32x16_bf16 v[18:33], v[178:181], v[170:173], v[18:33]
	v_mfma_f32_32x32x16_bf16 v[2:17], v[178:181], v[174:177], v[2:17]
	s_waitcnt lgkmcnt(0)
	v_mfma_f32_32x32x16_bf16 v[50:65], v[182:185], v[186:189], v[50:65]
	v_mfma_f32_32x32x16_bf16 v[34:49], v[182:185], v[190:193], v[34:49]
	v_mfma_f32_32x32x16_bf16 v[18:33], v[194:197], v[186:189], v[18:33]
	v_mfma_f32_32x32x16_bf16 v[2:17], v[194:197], v[190:193], v[2:17]
	s_cmp_lt_u32 s3, 14
	s_waitcnt lgkmcnt(0)
	s_barrier
; #define TIDX (tid_launder())
; DI int crow(int reg, int hh) { return (reg & 3) + 8 * (reg >> 2) + 4 * hh; }
; template <int NJ>
; DI void acc_to_ct(const f32x16 (&acc)[2][NJ], float* Ct) {
;   const int lane = TIDX & 63, wid = TIDX >> 6, wm = wid >> 1, wn = wid & 1;
;   const int r = lane & 31, hh = lane >> 5;
; #pragma unroll
;   for (int i = 0; i < 2; ++i)
; #pragma unroll
;     for (int j = 0; j < NJ; ++j)
; #pragma unroll
;       for (int e = 0; e < 16; ++e) Ct[(wm * 64 + i * 32 + crow(e, hh)) * 132 + wn * 32 * NJ + j * 32 + r] = acc[i][j][e];
;   __syncthreads();
; DI void outproj_tile(const Params& p, int l, int mt, int tn, char* smem) {
;     ...
;   float* Ct = (float*)smem;
;   acc_to_ct<2>(acc, Ct);
;   const float* xo = l == 0 ? p.x_in : p.out;
;   {
;     const int tid = TIDX, c = (tid & 31) * 4, row0 = tid >> 5;
;     float4 xa[16];
; #pragma unroll
;     for (int q = 0; q < 16; ++q) xa[q] = *(const float4*)(xo + (size_t)(m0 + row0 + 8 * q) * 1024 + tn * 128 + c);
; #pragma unroll
;     for (int q = 0; q < 16; ++q) {
;       const float4 cc = *(const float4*)(Ct + (row0 + 8 * q) * 132 + c);
	v_mov_b32_e32 v0, v230
	s_waitcnt vmcnt(1)
	v_mov_b32_e32 v66, v230
	v_and_b32_e32 v67, 31, v0
	v_lshrrev_b32_e32 v0, 3, v0
	v_and_b32_e32 v0, 4, v0
	v_lshrrev_b32_e32 v68, 1, v66
	v_and_or_b32 v0, v68, s47, v0
	v_and_or_b32 v66, v66, 64, v67
	v_mul_lo_u32 v0, v0, s79
	v_lshl_add_u32 v0, v66, 2, v0
	ds_write2_b32 v0, v50, v34 offset1:32
	ds_write2_b32 v0, v51, v35 offset0:132 offset1:164
	v_add_u32_e32 v34, 0x400, v0
	ds_write2_b32 v34, v52, v36 offset0:8 offset1:40
	ds_write2_b32 v34, v53, v37 offset0:140 offset1:172
	v_add_u32_e32 v34, 0x1000, v0
	ds_write2_b32 v34, v54, v38 offset0:32 offset1:64
	ds_write2_b32 v34, v55, v39 offset0:164 offset1:196
	v_add_u32_e32 v34, 0x1400, v0
	ds_write2_b32 v34, v56, v40 offset0:40 offset1:72
	ds_write2_b32 v34, v57, v41 offset0:172 offset1:204
	v_add_u32_e32 v34, 0x2000, v0
	ds_write2_b32 v34, v58, v42 offset0:64 offset1:96
	ds_write2_b32 v34, v59, v43 offset0:196 offset1:228
	v_add_u32_e32 v34, 0x2400, v0
	ds_write2_b32 v34, v60, v44 offset0:72 offset1:104
	ds_write2_b32 v34, v61, v45 offset0:204 offset1:236
	v_add_u32_e32 v34, 0x3000, v0
	ds_write2_b32 v34, v62, v46 offset0:96 offset1:128
	v_add_u32_e32 v34, 0x3200, v0
	ds_write2_b32 v34, v63, v47 offset0:100 offset1:132
	v_add_u32_e32 v34, 0x3400, v0
	ds_write2_b32 v34, v64, v48 offset0:104 offset1:136
	v_add_u32_e32 v34, 0x3600, v0
	ds_write2_b32 v34, v65, v49 offset0:108 offset1:140
	v_add_u32_e32 v34, 0x4000, v0
	ds_write2_b32 v34, v18, v2 offset0:128 offset1:160
	v_add_u32_e32 v2, 0x4400, v0
	ds_write2_b32 v2, v19, v3 offset0:4 offset1:36
	ds_write2_b32 v2, v20, v4 offset0:136 offset1:168
	v_add_u32_e32 v2, 0x4800, v0
	ds_write2_b32 v2, v21, v5 offset0:12 offset1:44
	v_add_u32_e32 v2, 0x5000, v0
	ds_write2_b32 v2, v22, v6 offset0:160 offset1:192
	v_add_u32_e32 v2, 0x5400, v0
	ds_write2_b32 v2, v23, v7 offset0:36 offset1:68
	ds_write2_b32 v2, v24, v8 offset0:168 offset1:200
	v_add_u32_e32 v2, 0x5800, v0
	ds_write2_b32 v2, v25, v9 offset0:44 offset1:76
	v_add_u32_e32 v2, 0x6000, v0
	ds_write2_b32 v2, v26, v10 offset0:192 offset1:224
	v_add_u32_e32 v2, 0x6400, v0
	ds_write2_b32 v2, v27, v11 offset0:68 offset1:100
	ds_write2_b32 v2, v28, v12 offset0:200 offset1:232
	v_add_u32_e32 v2, 0x6800, v0
	ds_write2_b32 v2, v29, v13 offset0:76 offset1:108
	v_add_u32_e32 v2, 0x7200, v0
	ds_write2_b32 v2, v30, v14 offset0:96 offset1:128
	v_add_u32_e32 v2, 0x7400, v0
	ds_write2_b32 v2, v31, v15 offset0:100 offset1:132
	v_add_u32_e32 v2, 0x7600, v0
	v_add_u32_e32 v0, 0x7800, v0
	ds_write2_b32 v0, v33, v17 offset0:108 offset1:140
	v_mov_b32_e32 v0, v230
	ds_write2_b32 v2, v32, v16 offset0:104 offset1:136
	s_waitcnt lgkmcnt(0)
	s_barrier
	s_lshl_b32 s14, s2, 2
	v_ashrrev_i32_e32 v68, 5, v0
	v_readlane_b32 s2, v254, 3
	v_add_u32_e32 v2, s1, v68
	v_readlane_b32 s3, v254, 4
	s_add_u32 s2, s2, s14
	v_lshlrev_b32_e32 v0, 4, v0
	s_addc_u32 s3, s3, 0
	v_and_b32_e32 v0, 0x1f0, v0
	v_ashrrev_i32_e32 v3, 31, v2
	v_lshl_add_u64 v[4:5], s[2:3], 0, v[0:1]
	v_lshlrev_b64 v[8:9], 12, v[2:3]
	s_mov_b64 s[2:3], 0x18000
	v_lshl_add_u64 v[20:21], v[8:9], 0, s[2:3]
	s_mov_b64 s[2:3], 0x20000
	v_lshl_add_u64 v[24:25], v[8:9], 0, s[2:3]
	s_mov_b64 s[2:3], 0x28000
	v_lshl_add_u64 v[28:29], v[8:9], 0, s[2:3]
	s_mov_b64 s[2:3], 0x30000
	v_lshl_add_u64 v[32:33], v[8:9], 0, s[2:3]
	s_mov_b64 s[2:3], 0x38000
	v_lshl_add_u64 v[36:37], v[8:9], 0, s[2:3]
	s_mov_b64 s[2:3], 0x40000
	v_lshl_add_u64 v[40:41], v[8:9], 0, s[2:3]
	s_mov_b64 s[2:3], 0x48000
	v_lshl_add_u64 v[44:45], v[8:9], 0, s[2:3]
	s_mov_b64 s[2:3], 0x50000
	v_lshl_add_u64 v[48:49], v[8:9], 0, s[2:3]
	s_mov_b64 s[2:3], 0x58000
	v_lshl_add_u64 v[52:53], v[8:9], 0, s[2:3]
	s_mov_b64 s[2:3], 0x60000
	v_lshl_add_u64 v[56:57], v[8:9], 0, s[2:3]
	s_mov_b64 s[2:3], 0x68000
	v_lshl_add_u64 v[60:61], v[8:9], 0, s[2:3]
	s_mov_b64 s[2:3], 0x70000
	v_lshl_add_u64 v[64:65], v[8:9], 0, s[2:3]
	s_mov_b64 s[2:3], 0x78000
	v_readlane_b32 s16, v252, 9
	v_lshl_add_u64 v[12:13], v[8:9], 0, s[48:49]
	v_lshl_add_u64 v[16:17], v[8:9], 0, s[40:41]
	v_lshl_add_u64 v[66:67], v[8:9], 0, s[2:3]
	v_readlane_b32 s22, v252, 15
	v_readlane_b32 s23, v252, 16
	v_lshl_add_u64 v[62:63], v[4:5], 0, v[8:9]
	v_lshl_add_u64 v[58:59], v[4:5], 0, v[12:13]
	v_lshl_add_u64 v[54:55], v[4:5], 0, v[16:17]
	v_lshl_add_u64 v[50:51], v[4:5], 0, v[20:21]
	v_lshl_add_u64 v[46:47], v[4:5], 0, v[24:25]
	v_lshl_add_u64 v[42:43], v[4:5], 0, v[28:29]
	v_lshl_add_u64 v[38:39], v[4:5], 0, v[32:33]
	v_lshl_add_u64 v[34:35], v[4:5], 0, v[36:37]
	v_lshl_add_u64 v[30:31], v[4:5], 0, v[40:41]
	v_lshl_add_u64 v[26:27], v[4:5], 0, v[44:45]
	v_lshl_add_u64 v[22:23], v[4:5], 0, v[48:49]
	v_lshl_add_u64 v[18:19], v[4:5], 0, v[52:53]
	v_lshl_add_u64 v[14:15], v[4:5], 0, v[56:57]
	v_lshl_add_u64 v[10:11], v[4:5], 0, v[60:61]
	v_lshl_add_u64 v[6:7], v[4:5], 0, v[64:65]
	v_lshl_add_u64 v[2:3], v[4:5], 0, v[66:67]
	v_lshl_add_u64 v[4:5], s[22:23], 0, v[8:9]
	v_lshl_add_u64 v[4:5], v[4:5], 0, s[14:15]
	v_lshl_add_u64 v[96:97], v[4:5], 0, v[0:1]
	v_lshl_add_u64 v[4:5], s[22:23], 0, v[12:13]
	v_lshl_add_u64 v[4:5], v[4:5], 0, s[14:15]
	v_lshl_add_u64 v[94:95], v[4:5], 0, v[0:1]
	v_lshl_add_u64 v[4:5], s[22:23], 0, v[16:17]
	v_lshl_add_u64 v[4:5], v[4:5], 0, s[14:15]
	v_lshl_add_u64 v[92:93], v[4:5], 0, v[0:1]
	v_lshl_add_u64 v[4:5], s[22:23], 0, v[20:21]
	v_lshl_add_u64 v[4:5], v[4:5], 0, s[14:15]
	v_lshl_add_u64 v[90:91], v[4:5], 0, v[0:1]
	v_lshl_add_u64 v[4:5], s[22:23], 0, v[24:25]
	v_lshl_add_u64 v[4:5], v[4:5], 0, s[14:15]
	v_lshl_add_u64 v[88:89], v[4:5], 0, v[0:1]
	v_lshl_add_u64 v[4:5], s[22:23], 0, v[28:29]
	v_lshl_add_u64 v[4:5], v[4:5], 0, s[14:15]
	v_lshl_add_u64 v[86:87], v[4:5], 0, v[0:1]
	v_lshl_add_u64 v[4:5], s[22:23], 0, v[32:33]
	v_lshl_add_u64 v[4:5], v[4:5], 0, s[14:15]
	v_lshl_add_u64 v[84:85], v[4:5], 0, v[0:1]
	v_lshl_add_u64 v[4:5], s[22:23], 0, v[36:37]
	v_lshl_add_u64 v[4:5], v[4:5], 0, s[14:15]
	v_lshl_add_u64 v[82:83], v[4:5], 0, v[0:1]
	v_lshl_add_u64 v[4:5], s[22:23], 0, v[40:41]
	v_lshl_add_u64 v[4:5], v[4:5], 0, s[14:15]
	v_lshl_add_u64 v[80:81], v[4:5], 0, v[0:1]
	v_lshl_add_u64 v[4:5], s[22:23], 0, v[44:45]
	v_lshl_add_u64 v[4:5], v[4:5], 0, s[14:15]
	v_lshl_add_u64 v[78:79], v[4:5], 0, v[0:1]
	v_lshl_add_u64 v[4:5], s[22:23], 0, v[48:49]
	v_lshl_add_u64 v[4:5], v[4:5], 0, s[14:15]
	v_lshl_add_u64 v[76:77], v[4:5], 0, v[0:1]
	v_lshl_add_u64 v[4:5], s[22:23], 0, v[52:53]
	v_lshl_add_u64 v[4:5], v[4:5], 0, s[14:15]
	v_lshl_add_u64 v[74:75], v[4:5], 0, v[0:1]
	v_lshl_add_u64 v[4:5], s[22:23], 0, v[56:57]
	v_lshl_add_u64 v[4:5], v[4:5], 0, s[14:15]
	s_waitcnt vmcnt(0)
; #define TIDX (tid_launder())
; DI void outproj_tile(const Params& p, int l, int mt, int tn, char* smem) {
;     ...
;     const int tid = TIDX, c = (tid & 31) * 4, row0 = tid >> 5;
;     float4 xa[16];
; #pragma unroll
;     for (int q = 0; q < 16; ++q) xa[q] = *(const float4*)(xo + (size_t)(m0 + row0 + 8 * q) * 1024 + tn * 128 + c);
; #pragma unroll
;     for (int q = 0; q < 16; ++q) {
;       const float4 cc = *(const float4*)(Ct + (row0 + 8 * q) * 132 + c);
;       *(float4*)(p.out + (size_t)(m0 + row0 + 8 * q) * 1024 + tn * 128 + c) = make_float4(xa[q].x + cc.x, xa[q].y + cc.y, xa[q].z + cc.z, xa[q].w + cc.w);
;     }
;   }
;   __syncthreads();
	v_lshl_add_u64 v[72:73], v[4:5], 0, v[0:1]
	v_lshl_add_u64 v[4:5], s[22:23], 0, v[60:61]
	v_lshl_add_u64 v[4:5], v[4:5], 0, s[14:15]
	v_lshl_add_u64 v[70:71], v[4:5], 0, v[0:1]
	v_lshl_add_u64 v[4:5], s[22:23], 0, v[64:65]
	v_lshl_add_u64 v[4:5], v[4:5], 0, s[14:15]
	v_mad_u64_u32 v[98:99], s[2:3], v68, s79, v[0:1]
	v_lshl_add_u64 v[68:69], v[4:5], 0, v[0:1]
	v_lshl_add_u64 v[4:5], s[22:23], 0, v[66:67]
	v_lshl_add_u64 v[4:5], v[4:5], 0, s[14:15]
	v_lshl_add_u64 v[66:67], v[4:5], 0, v[0:1]
	global_load_dwordx4 v[2:5], v[2:3], off
	ds_read_b128 v[100:103], v98 offset:63360
	global_load_dwordx4 v[6:9], v[6:7], off
	v_readlane_b32 s1, v250, 60
	global_load_dwordx4 v[10:13], v[10:11], off
	s_add_i32 s0, s0, s1
	global_load_dwordx4 v[14:17], v[14:15], off
	s_cmpk_gt_u32 s0, 0xff
	global_load_dwordx4 v[18:21], v[18:19], off
	v_readlane_b32 s17, v252, 10
	global_load_dwordx4 v[22:25], v[22:23], off
	v_readlane_b32 s18, v252, 11
	global_load_dwordx4 v[26:29], v[26:27], off
	v_readlane_b32 s19, v252, 12
	global_load_dwordx4 v[30:33], v[30:31], off
	v_readlane_b32 s20, v252, 13
	global_load_dwordx4 v[34:37], v[34:35], off
	v_readlane_b32 s21, v252, 14
	global_load_dwordx4 v[38:41], v[38:39], off
	v_readlane_b32 s24, v252, 17
	global_load_dwordx4 v[42:45], v[42:43], off
	v_readlane_b32 s25, v252, 18
	global_load_dwordx4 v[46:49], v[46:47], off
	v_readlane_b32 s26, v252, 19
	global_load_dwordx4 v[50:53], v[50:51], off
	v_readlane_b32 s27, v252, 20
	global_load_dwordx4 v[54:57], v[54:55], off
	v_readlane_b32 s28, v252, 21
	global_load_dwordx4 v[58:61], v[58:59], off
	v_readlane_b32 s29, v252, 22
	global_load_dwordx4 v[62:65], v[62:63], off
	v_readlane_b32 s30, v252, 23
	v_readlane_b32 s31, v252, 24
	s_waitcnt vmcnt(15) lgkmcnt(0)
	v_pk_add_f32 v[2:3], v[2:3], v[100:101]
	v_pk_add_f32 v[4:5], v[4:5], v[102:103]
	ds_read_b128 v[100:103], v98 offset:59136
	s_waitcnt vmcnt(14) lgkmcnt(0)
	v_pk_add_f32 v[6:7], v[6:7], v[100:101]
	v_pk_add_f32 v[8:9], v[8:9], v[102:103]
	ds_read_b128 v[100:103], v98 offset:54912
	s_waitcnt vmcnt(13) lgkmcnt(0)
	v_pk_add_f32 v[10:11], v[10:11], v[100:101]
	v_pk_add_f32 v[12:13], v[12:13], v[102:103]
	ds_read_b128 v[100:103], v98 offset:50688
	s_waitcnt vmcnt(12) lgkmcnt(0)
	v_pk_add_f32 v[14:15], v[14:15], v[100:101]
	v_pk_add_f32 v[16:17], v[16:17], v[102:103]
	ds_read_b128 v[100:103], v98 offset:46464
	s_waitcnt vmcnt(11) lgkmcnt(0)
	v_pk_add_f32 v[18:19], v[18:19], v[100:101]
	v_pk_add_f32 v[20:21], v[20:21], v[102:103]
	ds_read_b128 v[100:103], v98 offset:42240
	s_waitcnt vmcnt(10) lgkmcnt(0)
	v_pk_add_f32 v[22:23], v[22:23], v[100:101]
	v_pk_add_f32 v[24:25], v[24:25], v[102:103]
	ds_read_b128 v[100:103], v98 offset:38016
	s_waitcnt vmcnt(9) lgkmcnt(0)
	v_pk_add_f32 v[26:27], v[26:27], v[100:101]
	v_pk_add_f32 v[28:29], v[28:29], v[102:103]
	ds_read_b128 v[100:103], v98 offset:33792
	s_waitcnt vmcnt(8) lgkmcnt(0)
	v_pk_add_f32 v[30:31], v[30:31], v[100:101]
	v_pk_add_f32 v[32:33], v[32:33], v[102:103]
	ds_read_b128 v[100:103], v98 offset:29568
	s_waitcnt vmcnt(7) lgkmcnt(0)
	v_pk_add_f32 v[34:35], v[34:35], v[100:101]
	v_pk_add_f32 v[36:37], v[36:37], v[102:103]
	ds_read_b128 v[100:103], v98 offset:25344
	s_waitcnt vmcnt(6) lgkmcnt(0)
	v_pk_add_f32 v[38:39], v[38:39], v[100:101]
	v_pk_add_f32 v[40:41], v[40:41], v[102:103]
	ds_read_b128 v[100:103], v98 offset:21120
	s_waitcnt vmcnt(5) lgkmcnt(0)
	v_pk_add_f32 v[42:43], v[42:43], v[100:101]
	v_pk_add_f32 v[44:45], v[44:45], v[102:103]
	ds_read_b128 v[100:103], v98 offset:16896
	s_waitcnt vmcnt(4) lgkmcnt(0)
	v_pk_add_f32 v[46:47], v[46:47], v[100:101]
	v_pk_add_f32 v[48:49], v[48:49], v[102:103]
	ds_read_b128 v[100:103], v98 offset:12672
	s_waitcnt vmcnt(3) lgkmcnt(0)
	v_pk_add_f32 v[50:51], v[50:51], v[100:101]
	v_pk_add_f32 v[52:53], v[52:53], v[102:103]
	ds_read_b128 v[100:103], v98 offset:8448
	s_waitcnt vmcnt(2) lgkmcnt(0)
	v_pk_add_f32 v[54:55], v[54:55], v[100:101]
	v_pk_add_f32 v[56:57], v[56:57], v[102:103]
	ds_read_b128 v[100:103], v98 offset:4224
	s_waitcnt vmcnt(1) lgkmcnt(0)
	v_pk_add_f32 v[58:59], v[58:59], v[100:101]
	ds_read_b128 v[98:101], v98
	v_pk_add_f32 v[60:61], v[60:61], v[102:103]
	s_waitcnt vmcnt(0) lgkmcnt(0)
	v_pk_add_f32 v[62:63], v[62:63], v[98:99]
	v_pk_add_f32 v[64:65], v[64:65], v[100:101]
	global_store_dwordx4 v[96:97], v[62:65], off
	global_store_dwordx4 v[94:95], v[58:61], off
	global_store_dwordx4 v[92:93], v[54:57], off
	global_store_dwordx4 v[90:91], v[50:53], off
	global_store_dwordx4 v[88:89], v[46:49], off
	global_store_dwordx4 v[86:87], v[42:45], off
	global_store_dwordx4 v[84:85], v[38:41], off
	global_store_dwordx4 v[82:83], v[34:37], off
	global_store_dwordx4 v[80:81], v[30:33], off
	global_store_dwordx4 v[78:79], v[26:29], off
	global_store_dwordx4 v[76:77], v[22:25], off
	global_store_dwordx4 v[74:75], v[18:21], off
	global_store_dwordx4 v[72:73], v[14:17], off
	global_store_dwordx4 v[70:71], v[10:13], off
	global_store_dwordx4 v[68:69], v[6:9], off
	global_store_dwordx4 v[66:67], v[2:5], off
	s_barrier
	s_cbranch_scc0 .LBB0_11

; #define G_STORE(ST, S, unused) do { char* d_ = smem + (ST) * STAGE; \
;     *(uint4*)(d_ + alo[0]) = S##a0; *(uint4*)(d_ + alo[1]) = S##a1; *(uint4*)(d_ + alo[2]) = S##a2; *(uint4*)(d_ + alo[3]) = S##a3; \
;     *(uint4*)(d_ + blo[0]) = S##b0; *(uint4*)(d_ + blo[1]) = S##b1; \
;     if (NBCH == 4) { *(uint4*)(d_ + blo[NBCH - 2]) = S##b2; *(uint4*)(d_ + blo[NBCH - 1]) = S##b3; } } while (0)
; template <int NJ, class RowA>
; DI void gemm_main(f32x16 (&acc)[2][NJ], const bf16_t* __restrict__ A, RowA rowA, size_t kstrideA, int m0, int Mmax,
;                   const bf16_t* __restrict__ Bt, size_t ldb, int n0, int nk, char* smem) {
;     ...
;   __syncthreads();
;   G_LOAD(x0, 0, 0);
;   G_LOAD(x1, 0, 1);
;   G_STORE(0, x0, 0);
;   __syncthreads();
; #pragma unroll 1
;   for (int kt = 0; kt < nk; kt += 2) {
;     G_LOAD(x0, 0, (kt + 2 < nk ? kt + 2 : nk - 1));
;     G_COMPUTE(0);
;     G_STORE(1, x1, 0);
;     __syncthreads();
;     G_LOAD(x1, 0, (kt + 3 < nk ? kt + 3 : nk - 1));
;     G_COMPUTE(1);
;     G_STORE(0, x0, 0);
;     __syncthreads();
.LBB0_19:
	s_cmp_lt_i32 s4, 12
	s_cbranch_scc0 .Lpeel_tail_19
	ds_read_b128 v[176:179], v0
	ds_read_b128 v[180:183], v71 offset:18432
	ds_read_b128 v[184:187], v0 offset:4608
	s_add_i32 s5, s4, 4
	s_min_u32 s5, s5, 15
	s_lshl_b32 s14, s5, 7
	v_lshl_add_u64 v[78:79], v[58:59], 0, s[14:15]
	v_lshl_add_u64 v[82:83], v[60:61], 0, s[14:15]
	v_lshl_add_u64 v[86:87], v[62:63], 0, s[14:15]
	v_lshl_add_u64 v[122:123], v[64:65], 0, s[14:15]
	v_lshl_add_u64 v[126:127], v[66:67], 0, s[14:15]
	v_lshl_add_u64 v[130:131], v[68:69], 0, s[14:15]
	s_add_i32 s4, s4, 2
	ds_read_b128 v[188:191], v0 offset:32
	ds_read_b128 v[192:195], v71 offset:18464
	ds_read_b128 v[196:199], v0 offset:4640
	s_waitcnt lgkmcnt(3)
	v_mfma_f32_32x32x16_bf16 v[18:33], v[176:179], v[180:183], v[18:33]
	global_load_dwordx4 v[78:81], v[78:79], off
	s_nop 0
	global_load_dwordx4 v[82:85], v[82:83], off
	v_mfma_f32_32x32x16_bf16 v[2:17], v[184:187], v[180:183], v[2:17]
	global_load_dwordx4 v[86:89], v[86:87], off
	ds_read_b128 v[176:179], v0 offset:64
	ds_read_b128 v[180:183], v71 offset:18496
	ds_read_b128 v[184:187], v0 offset:4672
	s_waitcnt lgkmcnt(3)
	v_mfma_f32_32x32x16_bf16 v[18:33], v[188:191], v[192:195], v[18:33]
	global_load_dwordx4 v[122:125], v[122:123], off
	s_nop 0
	global_load_dwordx4 v[126:129], v[126:127], off
	v_mfma_f32_32x32x16_bf16 v[2:17], v[196:199], v[192:195], v[2:17]
	global_load_dwordx4 v[130:133], v[130:131], off
	ds_read_b128 v[188:191], v0 offset:96
	ds_read_b128 v[192:195], v71 offset:18528
	ds_read_b128 v[196:199], v0 offset:4704
	s_waitcnt lgkmcnt(3)
	v_mfma_f32_32x32x16_bf16 v[18:33], v[176:179], v[180:183], v[18:33]
	s_waitcnt vmcnt(6)
	ds_write_b128 v70, v[34:37] offset:27648
	ds_write_b128 v72, v[38:41] offset:27648
	v_mfma_f32_32x32x16_bf16 v[2:17], v[184:187], v[180:183], v[2:17]
	ds_write_b128 v74, v[42:45] offset:27648
	s_waitcnt lgkmcnt(3)
	v_mfma_f32_32x32x16_bf16 v[18:33], v[188:191], v[192:195], v[18:33]
	ds_write_b128 v76, v[54:57] offset:27648
	ds_write_b128 v70, v[46:49] offset:46080
	v_mfma_f32_32x32x16_bf16 v[2:17], v[196:199], v[192:195], v[2:17]
	ds_write_b128 v72, v[50:53] offset:46080
	s_min_u32 s5, s4, 12
	s_lshl_b32 s14, s5, 7
	v_lshl_add_u64 v[34:35], v[58:59], 0, s[14:15]
	v_lshl_add_u64 v[38:39], v[60:61], 0, s[14:15]
	v_lshl_add_u64 v[42:43], v[62:63], 0, s[14:15]
	v_lshl_add_u64 v[46:47], v[64:65], 0, s[14:15]
	v_lshl_add_u64 v[48:49], v[66:67], 0, s[14:15]
	v_lshl_add_u64 v[50:51], v[68:69], 0, s[14:15]
	s_waitcnt lgkmcnt(0)
	s_barrier
	ds_read_b128 v[176:179], v0 offset:27648
	ds_read_b128 v[180:183], v71 offset:46080
	ds_read_b128 v[184:187], v0 offset:32256
	ds_read_b128 v[188:191], v0 offset:27680
	ds_read_b128 v[192:195], v71 offset:46112
	ds_read_b128 v[196:199], v0 offset:32288
	s_waitcnt lgkmcnt(3)
	v_mfma_f32_32x32x16_bf16 v[18:33], v[176:179], v[180:183], v[18:33]
	global_load_dwordx4 v[34:37], v[34:35], off offset:384
	s_nop 0
	global_load_dwordx4 v[38:41], v[38:39], off offset:384
	v_mfma_f32_32x32x16_bf16 v[2:17], v[184:187], v[180:183], v[2:17]
	global_load_dwordx4 v[42:45], v[42:43], off offset:384
	ds_read_b128 v[176:179], v0 offset:27712
	ds_read_b128 v[180:183], v71 offset:46144
	ds_read_b128 v[184:187], v0 offset:32320
	s_waitcnt lgkmcnt(3)
	v_mfma_f32_32x32x16_bf16 v[18:33], v[188:191], v[192:195], v[18:33]
	global_load_dwordx4 v[54:57], v[46:47], off offset:384
	s_nop 0
	global_load_dwordx4 v[46:49], v[48:49], off offset:384
	v_mfma_f32_32x32x16_bf16 v[2:17], v[196:199], v[192:195], v[2:17]
	global_load_dwordx4 v[50:53], v[50:51], off offset:384
	ds_read_b128 v[188:191], v0 offset:27744
	ds_read_b128 v[192:195], v71 offset:46176
	ds_read_b128 v[196:199], v0 offset:32352
	s_waitcnt lgkmcnt(3)
	v_mfma_f32_32x32x16_bf16 v[18:33], v[176:179], v[180:183], v[18:33]
	s_waitcnt vmcnt(6)
	ds_write_b128 v70, v[78:81]
	ds_write_b128 v72, v[82:85]
	v_mfma_f32_32x32x16_bf16 v[2:17], v[184:187], v[180:183], v[2:17]
	ds_write_b128 v74, v[86:89]
	s_waitcnt lgkmcnt(3)
	v_mfma_f32_32x32x16_bf16 v[18:33], v[188:191], v[192:195], v[18:33]
	ds_write_b128 v76, v[122:125]
	ds_write_b128 v70, v[126:129] offset:18432
	v_mfma_f32_32x32x16_bf16 v[2:17], v[196:199], v[192:195], v[2:17]
	ds_write_b128 v72, v[130:133] offset:18432
	s_cmp_lt_u32 s4, 14
	s_waitcnt lgkmcnt(0)
	s_barrier
	s_branch .LBB0_19
; #define G_STORE(ST, S, unused) do { char* d_ = smem + (ST) * STAGE; \
;     *(uint4*)(d_ + alo[0]) = S##a0; *(uint4*)(d_ + alo[1]) = S##a1; *(uint4*)(d_ + alo[2]) = S##a2; *(uint4*)(d_ + alo[3]) = S##a3; \
;     *(uint4*)(d_ + blo[0]) = S##b0; *(uint4*)(d_ + blo[1]) = S##b1; \
;     if (NBCH == 4) { *(uint4*)(d_ + blo[NBCH - 2]) = S##b2; *(uint4*)(d_ + blo[NBCH - 1]) = S##b3; } } while (0)
; template <int NJ, class RowA>
; DI void gemm_main(f32x16 (&acc)[2][NJ], const bf16_t* __restrict__ A, RowA rowA, size_t kstrideA, int m0, int Mmax,
;                   const bf16_t* __restrict__ Bt, size_t ldb, int n0, int nk, char* smem) {
;     ...
;   __syncthreads();
;   G_LOAD(x0, 0, 0);
;   G_LOAD(x1, 0, 1);
;   G_STORE(0, x0, 0);
;   __syncthreads();
; #pragma unroll 1
;   for (int kt = 0; kt < nk; kt += 2) {
;     G_LOAD(x0, 0, (kt + 2 < nk ? kt + 2 : nk - 1));
;     G_COMPUTE(0);
;     G_STORE(1, x1, 0);
;     __syncthreads();
;     G_LOAD(x1, 0, (kt + 3 < nk ? kt + 3 : nk - 1));
;     G_COMPUTE(1);
;     G_STORE(0, x0, 0);
;     __syncthreads();
; DI void merge_tile(const Params& p, int mt, int nt, char* smem) {
;     ...
;     const int koff = x == 0 ? 0 : (x == 1 ? 256 : 768);
;     const int nkp = x == 1 ? 8 : 4;
;     f32x16 ag[2][1], ap[2][1];
;     gemm_main<1>(ag, p.h, RowLin{1024}, 64, m0, T_TOK, p.wt_in + (size_t)(4224 + x * 1024) * 1024, 1024, n0, 16, smem);
;     gemm_main<1>(ap, p.projZ + koff, RowLin{LDA_Z}, 64, m0, T_TOK, p.wt_br + koff, 1024, n0, nkp, smem);
.Lpeel_tail_19:
	ds_read_b128 v[176:179], v0
	ds_read_b128 v[180:183], v71 offset:18432
	ds_read_b128 v[184:187], v0 offset:4608
	s_add_i32 s5, s4, 4
	s_min_u32 s5, s5, 15
	s_lshl_b32 s14, s5, 7
	v_lshl_add_u64 v[78:79], v[58:59], 0, s[14:15]
	v_lshl_add_u64 v[82:83], v[60:61], 0, s[14:15]
	v_lshl_add_u64 v[86:87], v[62:63], 0, s[14:15]
	v_lshl_add_u64 v[122:123], v[64:65], 0, s[14:15]
	v_lshl_add_u64 v[126:127], v[66:67], 0, s[14:15]
	v_lshl_add_u64 v[130:131], v[68:69], 0, s[14:15]
	s_add_i32 s4, s4, 2
	ds_read_b128 v[188:191], v0 offset:32
	ds_read_b128 v[192:195], v71 offset:18464
	ds_read_b128 v[196:199], v0 offset:4640
	s_waitcnt lgkmcnt(3)
	v_mfma_f32_32x32x16_bf16 v[18:33], v[176:179], v[180:183], v[18:33]
	v_mfma_f32_32x32x16_bf16 v[2:17], v[184:187], v[180:183], v[2:17]
	ds_read_b128 v[176:179], v0 offset:64
	ds_read_b128 v[180:183], v71 offset:18496
	ds_read_b128 v[184:187], v0 offset:4672
	s_waitcnt lgkmcnt(3)
	v_mfma_f32_32x32x16_bf16 v[18:33], v[188:191], v[192:195], v[18:33]
	v_mfma_f32_32x32x16_bf16 v[2:17], v[196:199], v[192:195], v[2:17]
	ds_read_b128 v[188:191], v0 offset:96
	ds_read_b128 v[192:195], v71 offset:18528
	ds_read_b128 v[196:199], v0 offset:4704
	s_waitcnt lgkmcnt(3)
	v_mfma_f32_32x32x16_bf16 v[18:33], v[176:179], v[180:183], v[18:33]
	s_waitcnt vmcnt(0)
	ds_write_b128 v70, v[34:37] offset:27648
	ds_write_b128 v72, v[38:41] offset:27648
	v_mfma_f32_32x32x16_bf16 v[2:17], v[184:187], v[180:183], v[2:17]
	ds_write_b128 v74, v[42:45] offset:27648
	s_waitcnt lgkmcnt(3)
	v_mfma_f32_32x32x16_bf16 v[18:33], v[188:191], v[192:195], v[18:33]
	ds_write_b128 v76, v[54:57] offset:27648
	ds_write_b128 v70, v[46:49] offset:46080
	v_mfma_f32_32x32x16_bf16 v[2:17], v[196:199], v[192:195], v[2:17]
	ds_write_b128 v72, v[50:53] offset:46080
	s_min_u32 s5, s4, 12
	s_lshl_b32 s14, s5, 7
	v_lshl_add_u64 v[34:35], v[58:59], 0, s[14:15]
	v_lshl_add_u64 v[38:39], v[60:61], 0, s[14:15]
	v_lshl_add_u64 v[42:43], v[62:63], 0, s[14:15]
	v_lshl_add_u64 v[46:47], v[64:65], 0, s[14:15]
	v_lshl_add_u64 v[48:49], v[66:67], 0, s[14:15]
	v_lshl_add_u64 v[50:51], v[68:69], 0, s[14:15]
	s_waitcnt lgkmcnt(0)
	s_barrier
	ds_read_b128 v[176:179], v0 offset:27648
	ds_read_b128 v[180:183], v71 offset:46080
	ds_read_b128 v[184:187], v0 offset:32256
	ds_read_b128 v[188:191], v0 offset:27680
	ds_read_b128 v[192:195], v71 offset:46112
	ds_read_b128 v[196:199], v0 offset:32288
	s_waitcnt lgkmcnt(3)
	v_mfma_f32_32x32x16_bf16 v[18:33], v[176:179], v[180:183], v[18:33]
	v_mfma_f32_32x32x16_bf16 v[2:17], v[184:187], v[180:183], v[2:17]
	ds_read_b128 v[176:179], v0 offset:27712
	ds_read_b128 v[180:183], v71 offset:46144
	ds_read_b128 v[184:187], v0 offset:32320
	s_waitcnt lgkmcnt(3)
	v_mfma_f32_32x32x16_bf16 v[18:33], v[188:191], v[192:195], v[18:33]
	v_mfma_f32_32x32x16_bf16 v[2:17], v[196:199], v[192:195], v[2:17]
	ds_read_b128 v[188:191], v0 offset:27744
	ds_read_b128 v[192:195], v71 offset:46176
	ds_read_b128 v[196:199], v0 offset:32352
	s_waitcnt lgkmcnt(3)
	v_mfma_f32_32x32x16_bf16 v[18:33], v[176:179], v[180:183], v[18:33]
	v_mfma_f32_32x32x16_bf16 v[2:17], v[184:187], v[180:183], v[2:17]
	s_waitcnt lgkmcnt(0)
	v_mfma_f32_32x32x16_bf16 v[18:33], v[188:191], v[192:195], v[18:33]
	v_mfma_f32_32x32x16_bf16 v[2:17], v[196:199], v[192:195], v[2:17]
	s_cmp_lt_u32 s4, 14
	s_waitcnt lgkmcnt(0)
	s_barrier
	s_cmp_eq_u32 s3, 1
	s_cselect_b32 s5, s42, 0x300
	s_cselect_b32 s4, 8, 4
	s_cmp_lg_u32 s3, 0
	v_mov_b32_e32 v58, v230
	s_cselect_b32 s5, s5, 0
	v_readlane_b32 s16, v252, 57
	s_lshl_b32 s5, s5, 1
	v_ashrrev_i32_e32 v59, 3, v58
	v_readlane_b32 s28, v253, 5
	s_waitcnt vmcnt(5)
	v_add_u32_e32 v36, s1, v59
	v_readlane_b32 s29, v253, 6
	s_add_u32 s6, s28, s5
	v_lshlrev_b32_e32 v0, 4, v58
	v_min_i32_e32 v36, 0x7fff, v36
	s_addc_u32 s7, s29, 0
	v_and_b32_e32 v0, 0x70, v0
	v_ashrrev_i32_e32 v37, 31, v36
	v_lshl_add_u64 v[34:35], s[6:7], 0, v[0:1]
	v_lshlrev_b64 v[36:37], 11, v[36:37]
	v_lshl_add_u64 v[122:123], v[34:35], 0, v[36:37]
	v_add_u32_e32 v36, 0x100, v58
	v_ashrrev_i32_e32 v60, 3, v36
	v_add_u32_e32 v36, s1, v60
	v_min_i32_e32 v36, 0x7fff, v36
	v_ashrrev_i32_e32 v37, 31, v36
	v_lshlrev_b64 v[36:37], 11, v[36:37]
	v_lshl_add_u64 v[124:125], v[34:35], 0, v[36:37]
	v_add_u32_e32 v36, 0x200, v58
	v_ashrrev_i32_e32 v61, 3, v36
	v_add_u32_e32 v36, s1, v61
	v_min_i32_e32 v36, 0x7fff, v36
	v_ashrrev_i32_e32 v37, 31, v36
	v_lshlrev_b64 v[36:37], 11, v[36:37]
	v_lshl_add_u64 v[126:127], v[34:35], 0, v[36:37]
	v_add_u32_e32 v36, 0x300, v58
	v_ashrrev_i32_e32 v62, 3, v36
	v_add_u32_e32 v36, s1, v62
	v_min_i32_e32 v36, 0x7fff, v36
	v_ashrrev_i32_e32 v37, 31, v36
	v_lshlrev_b64 v[36:37], 11, v[36:37]
	v_readlane_b32 s17, v252, 58
	s_add_u32 s8, s16, s5
	v_lshl_add_u64 v[128:129], v[34:35], 0, v[36:37]
	v_add_u32_e32 v36, s2, v59
	s_addc_u32 s9, s17, 0
	v_ashrrev_i32_e32 v37, 31, v36
	v_lshl_add_u64 v[34:35], s[8:9], 0, v[0:1]
	v_lshlrev_b64 v[36:37], 11, v[36:37]
	v_lshl_add_u64 v[130:131], v[34:35], 0, v[36:37]
	v_add_u32_e32 v36, s2, v60
	v_ashrrev_i32_e32 v37, 31, v36
	v_lshlrev_b64 v[36:37], 11, v[36:37]
	v_lshl_add_u64 v[132:133], v[34:35], 0, v[36:37]
	s_barrier
; #define G_STORE(ST, S, unused) do { char* d_ = smem + (ST) * STAGE; \
;     *(uint4*)(d_ + alo[0]) = S##a0; *(uint4*)(d_ + alo[1]) = S##a1; *(uint4*)(d_ + alo[2]) = S##a2; *(uint4*)(d_ + alo[3]) = S##a3; \
;     *(uint4*)(d_ + blo[0]) = S##b0; *(uint4*)(d_ + blo[1]) = S##b1; \
;     if (NBCH == 4) { *(uint4*)(d_ + blo[NBCH - 2]) = S##b2; *(uint4*)(d_ + blo[NBCH - 1]) = S##b3; } } while (0)
; template <int NJ, class RowA>
; DI void gemm_main(f32x16 (&acc)[2][NJ], const bf16_t* __restrict__ A, RowA rowA, size_t kstrideA, int m0, int Mmax,
;                   const bf16_t* __restrict__ Bt, size_t ldb, int n0, int nk, char* smem) {
;     ...
;   const bf16_t* ap[4]; const bf16_t* bp[NBCH]; int alo[4], blo[NBCH];
; #pragma unroll
;   for (int i = 0; i < 4; ++i) {
;     const int c = tid + 256 * i, row = c >> 3, kc = c & 7;
;     int m = m0 + row; m = m < Mmax ? m : Mmax - 1;
;     ap[i] = A + rowA(m) + kc * 8; alo[i] = row * 144 + kc * 16;
;   }
; #pragma unroll
;   for (int i = 0; i < NBCH; ++i) {
;     const int c = tid + 256 * i, row = c >> 3, kc = c & 7;
;     bp[i] = Bt + (size_t)(n0 + row) * ldb + kc * 8; blo[i] = 128 * 144 + row * 144 + kc * 16;
;   }
; #pragma unroll
;   for (int i = 0; i < 2; ++i)
; #pragma unroll
;     for (int j = 0; j < NJ; ++j)
; #pragma unroll
;       for (int e = 0; e < 16; ++e) acc[i][j][e] = 0.f;
;   uint4 x0a0, x0a1, x0a2, x0a3, x0b0, x0b1, x0b2, x0b3, x1a0, x1a1, x1a2, x1a3, x1b0, x1b1, x1b2, x1b3;
;   x0b2 = x0b3 = x1b2 = x1b3 = make_uint4(0, 0, 0, 0);
;     ...
;   __syncthreads();
;   G_LOAD(x0, 0, 0);
;   G_LOAD(x1, 0, 1);
;   G_STORE(0, x0, 0);
;   __syncthreads();
; #pragma unroll 1
;   for (int kt = 0; kt < nk; kt += 2) {
;     G_LOAD(x0, 0, (kt + 2 < nk ? kt + 2 : nk - 1));
;     G_COMPUTE(0);
;     G_STORE(1, x1, 0);
;     __syncthreads();
;     G_LOAD(x1, 0, (kt + 3 < nk ? kt + 3 : nk - 1));
;     G_COMPUTE(1);
;     G_STORE(0, x0, 0);
;     __syncthreads();
	global_load_dwordx4 v[34:37], v[122:123], off
	global_load_dwordx4 v[38:41], v[124:125], off
	global_load_dwordx4 v[42:45], v[126:127], off
	global_load_dwordx4 v[46:49], v[128:129], off
	global_load_dwordx4 v[50:53], v[130:131], off
	global_load_dwordx4 v[54:57], v[132:133], off
	global_load_dwordx4 v[66:69], v[122:123], off offset:128
	global_load_dwordx4 v[70:73], v[124:125], off offset:128
	global_load_dwordx4 v[74:77], v[126:127], off offset:128
	global_load_dwordx4 v[78:81], v[128:129], off offset:128
	global_load_dwordx4 v[82:85], v[130:131], off offset:128
	global_load_dwordx4 v[86:89], v[132:133], off offset:128
	v_and_b32_e32 v63, 31, v58
	v_lshrrev_b32_e32 v58, 1, v58
	v_and_or_b32 v64, v58, s47, v63
	v_and_b32_e32 v65, 16, v58
	v_and_or_b32 v58, v58, 32, v63
	v_mad_u64_u32 v[134:135], s[6:7], v59, s76, v[0:1]
	v_mad_u64_u32 v[136:137], s[6:7], v60, s76, v[0:1]
	v_mad_u64_u32 v[138:139], s[6:7], v61, s76, v[0:1]
	v_mad_u64_u32 v[140:141], s[6:7], v62, s76, v[0:1]
	v_mul_u32_u24_e32 v58, 0x90, v58
	v_mul_lo_u32 v0, v64, s76
	s_mov_b32 s5, 3
	s_add_i32 s6, s4, -1
	v_add_u32_e32 v0, v65, v0
	v_add_u32_e32 v135, v58, v65
	v_readlane_b32 s18, v252, 59
	v_readlane_b32 s19, v252, 60
	v_readlane_b32 s20, v252, 61
	v_readlane_b32 s21, v252, 62
	v_readlane_b32 s22, v252, 63
	v_readlane_b32 s23, v253, 0
	v_readlane_b32 s24, v253, 1
	v_readlane_b32 s25, v253, 2
	v_readlane_b32 s26, v253, 3
	v_readlane_b32 s27, v253, 4
	v_readlane_b32 s30, v253, 7
	v_readlane_b32 s31, v253, 8
	s_waitcnt vmcnt(11)
	ds_write_b128 v134, v[34:37]
	s_waitcnt vmcnt(10)
	ds_write_b128 v136, v[38:41]
	s_waitcnt vmcnt(9)
	ds_write_b128 v138, v[42:45]
	s_waitcnt vmcnt(8)
	ds_write_b128 v140, v[46:49]
	s_waitcnt vmcnt(7)
	ds_write_b128 v134, v[50:53] offset:18432
	s_waitcnt vmcnt(6)
	ds_write_b128 v136, v[54:57] offset:18432
	v_mov_b32_e32 v34, 0
	v_mov_b32_e32 v35, v34
	v_mov_b32_e32 v36, v34
	v_mov_b32_e32 v37, v34
	v_mov_b32_e32 v38, v34
	v_mov_b32_e32 v39, v34
	v_mov_b32_e32 v40, v34
	v_mov_b32_e32 v41, v34
	v_mov_b32_e32 v42, v34
	v_mov_b32_e32 v43, v34
	v_mov_b32_e32 v44, v34
	v_mov_b32_e32 v45, v34
	v_mov_b32_e32 v46, v34
	v_mov_b32_e32 v47, v34
	v_mov_b32_e32 v48, v34
	v_mov_b32_e32 v49, v34
	v_mov_b32_e32 v50, v34
	v_mov_b32_e32 v51, v34
	v_mov_b32_e32 v52, v34
	v_mov_b32_e32 v53, v34
	v_mov_b32_e32 v54, v34
	v_mov_b32_e32 v55, v34
	v_mov_b32_e32 v56, v34
	v_mov_b32_e32 v57, v34
	v_mov_b32_e32 v58, v34
	v_mov_b32_e32 v59, v34
	v_mov_b32_e32 v60, v34
	v_mov_b32_e32 v61, v34
	v_mov_b32_e32 v62, v34
	v_mov_b32_e32 v63, v34
	v_mov_b32_e32 v64, v34
	v_mov_b32_e32 v65, v34
	s_waitcnt lgkmcnt(0)
	s_barrier
.LBB0_21:
	s_add_i32 s7, s5, -1
	s_cmp_lt_u32 s7, s4
	s_cbranch_scc0 .Lpeel_tail_21
	ds_read_b128 v[176:179], v0
	ds_read_b128 v[180:183], v135 offset:18432
	ds_read_b128 v[184:187], v0 offset:4608
	s_add_i32 s7, s5, -1
	s_min_u32 s14, s7, s6
	s_lshl_b64 s[8:9], s[14:15], 7
	v_lshl_add_u64 v[144:145], v[122:123], 0, s[8:9]
	v_lshl_add_u64 v[148:149], v[124:125], 0, s[8:9]
	v_lshl_add_u64 v[152:153], v[126:127], 0, s[8:9]
	v_lshl_add_u64 v[156:157], v[128:129], 0, s[8:9]
	v_lshl_add_u64 v[160:161], v[130:131], 0, s[8:9]
	v_lshl_add_u64 v[164:165], v[132:133], 0, s[8:9]
	ds_read_b128 v[188:191], v0 offset:32
	ds_read_b128 v[192:195], v135 offset:18464
	ds_read_b128 v[196:199], v0 offset:4640
	s_waitcnt lgkmcnt(3)
	v_mfma_f32_32x32x16_bf16 v[50:65], v[176:179], v[180:183], v[50:65]
	global_load_dwordx4 v[144:147], v[144:145], off
	s_nop 0
	global_load_dwordx4 v[148:151], v[148:149], off
	v_mfma_f32_32x32x16_bf16 v[34:49], v[184:187], v[180:183], v[34:49]
	global_load_dwordx4 v[152:155], v[152:153], off
	ds_read_b128 v[176:179], v0 offset:64
	ds_read_b128 v[180:183], v135 offset:18496
	ds_read_b128 v[184:187], v0 offset:4672
	s_waitcnt lgkmcnt(3)
	v_mfma_f32_32x32x16_bf16 v[50:65], v[188:191], v[192:195], v[50:65]
	global_load_dwordx4 v[156:159], v[156:157], off
	s_nop 0
	global_load_dwordx4 v[160:163], v[160:161], off
	v_mfma_f32_32x32x16_bf16 v[34:49], v[196:199], v[192:195], v[34:49]
	global_load_dwordx4 v[164:167], v[164:165], off
	ds_read_b128 v[188:191], v0 offset:96
	ds_read_b128 v[192:195], v135 offset:18528
	ds_read_b128 v[196:199], v0 offset:4704
	s_waitcnt lgkmcnt(3)
	v_mfma_f32_32x32x16_bf16 v[50:65], v[176:179], v[180:183], v[50:65]
	s_waitcnt vmcnt(6)
	ds_write_b128 v134, v[66:69] offset:27648
	ds_write_b128 v136, v[70:73] offset:27648
	v_mfma_f32_32x32x16_bf16 v[34:49], v[184:187], v[180:183], v[34:49]
	ds_write_b128 v138, v[74:77] offset:27648
	s_waitcnt lgkmcnt(3)
	v_mfma_f32_32x32x16_bf16 v[50:65], v[188:191], v[192:195], v[50:65]
	ds_write_b128 v140, v[78:81] offset:27648
	ds_write_b128 v134, v[82:85] offset:46080
	v_mfma_f32_32x32x16_bf16 v[34:49], v[196:199], v[192:195], v[34:49]
	ds_write_b128 v136, v[86:89] offset:46080
	s_min_u32 s14, s5, s6
	s_lshl_b64 s[8:9], s[14:15], 7
	v_lshl_add_u64 v[66:67], v[122:123], 0, s[8:9]
	v_lshl_add_u64 v[70:71], v[124:125], 0, s[8:9]
	v_lshl_add_u64 v[74:75], v[126:127], 0, s[8:9]
	v_lshl_add_u64 v[78:79], v[128:129], 0, s[8:9]
	v_lshl_add_u64 v[82:83], v[130:131], 0, s[8:9]
	v_lshl_add_u64 v[86:87], v[132:133], 0, s[8:9]
	s_waitcnt lgkmcnt(0)
	s_barrier
	ds_read_b128 v[176:179], v0 offset:27648
	ds_read_b128 v[180:183], v135 offset:46080
	ds_read_b128 v[184:187], v0 offset:32256
	ds_read_b128 v[188:191], v0 offset:27680
	ds_read_b128 v[192:195], v135 offset:46112
	ds_read_b128 v[196:199], v0 offset:32288
	s_waitcnt lgkmcnt(3)
	v_mfma_f32_32x32x16_bf16 v[50:65], v[176:179], v[180:183], v[50:65]
	global_load_dwordx4 v[66:69], v[66:67], off
	s_nop 0
	global_load_dwordx4 v[70:73], v[70:71], off
	v_mfma_f32_32x32x16_bf16 v[34:49], v[184:187], v[180:183], v[34:49]
	global_load_dwordx4 v[74:77], v[74:75], off
	ds_read_b128 v[176:179], v0 offset:27712
	ds_read_b128 v[180:183], v135 offset:46144
	ds_read_b128 v[184:187], v0 offset:32320
	s_waitcnt lgkmcnt(3)
	v_mfma_f32_32x32x16_bf16 v[50:65], v[188:191], v[192:195], v[50:65]
	global_load_dwordx4 v[78:81], v[78:79], off
	s_nop 0
	global_load_dwordx4 v[82:85], v[82:83], off
	v_mfma_f32_32x32x16_bf16 v[34:49], v[196:199], v[192:195], v[34:49]
	global_load_dwordx4 v[86:89], v[86:87], off
	ds_read_b128 v[188:191], v0 offset:27744
	ds_read_b128 v[192:195], v135 offset:46176
	ds_read_b128 v[196:199], v0 offset:32352
	s_waitcnt lgkmcnt(3)
	v_mfma_f32_32x32x16_bf16 v[50:65], v[176:179], v[180:183], v[50:65]
	s_waitcnt vmcnt(6)
	ds_write_b128 v134, v[144:147]
	ds_write_b128 v136, v[148:151]
	v_mfma_f32_32x32x16_bf16 v[34:49], v[184:187], v[180:183], v[34:49]
	ds_write_b128 v138, v[152:155]
	s_waitcnt lgkmcnt(3)
	v_mfma_f32_32x32x16_bf16 v[50:65], v[188:191], v[192:195], v[50:65]
	ds_write_b128 v140, v[156:159]
	ds_write_b128 v134, v[160:163] offset:18432
	v_mfma_f32_32x32x16_bf16 v[34:49], v[196:199], v[192:195], v[34:49]
	ds_write_b128 v136, v[164:167] offset:18432
	s_add_i32 s5, s5, 2
	s_cmp_lt_u32 s7, s4
	s_waitcnt lgkmcnt(0)
	s_barrier
	s_branch .LBB0_21
; DI float sigmoidf(float x) { return __builtin_amdgcn_rcpf(1.f + __expf(-x)); }
; #define G_STORE(ST, S, unused) do { char* d_ = smem + (ST) * STAGE; \
;     *(uint4*)(d_ + alo[0]) = S##a0; *(uint4*)(d_ + alo[1]) = S##a1; *(uint4*)(d_ + alo[2]) = S##a2; *(uint4*)(d_ + alo[3]) = S##a3; \
;     *(uint4*)(d_ + blo[0]) = S##b0; *(uint4*)(d_ + blo[1]) = S##b1; \
;     if (NBCH == 4) { *(uint4*)(d_ + blo[NBCH - 2]) = S##b2; *(uint4*)(d_ + blo[NBCH - 1]) = S##b3; } } while (0)
; template <int NJ, class RowA>
; DI void gemm_main(f32x16 (&acc)[2][NJ], const bf16_t* __restrict__ A, RowA rowA, size_t kstrideA, int m0, int Mmax,
;                   const bf16_t* __restrict__ Bt, size_t ldb, int n0, int nk, char* smem) {
;     ...
;   __syncthreads();
;   G_LOAD(x0, 0, 0);
;   G_LOAD(x1, 0, 1);
;   G_STORE(0, x0, 0);
;   __syncthreads();
; #pragma unroll 1
;   for (int kt = 0; kt < nk; kt += 2) {
;     G_LOAD(x0, 0, (kt + 2 < nk ? kt + 2 : nk - 1));
;     G_COMPUTE(0);
;     G_STORE(1, x1, 0);
;     __syncthreads();
;     G_LOAD(x1, 0, (kt + 3 < nk ? kt + 3 : nk - 1));
;     G_COMPUTE(1);
;     G_STORE(0, x0, 0);
;     __syncthreads();
; DI void merge_tile(const Params& p, int mt, int nt, char* smem) {
;     ...
;     gemm_main<1>(ap, p.projZ + koff, RowLin{LDA_Z}, 64, m0, T_TOK, p.wt_br + koff, 1024, n0, nkp, smem);
; #pragma unroll
;     for (int i = 0; i < 2; ++i)
; #pragma unroll
;       for (int e = 0; e < 16; ++e) mac[i][0][e] += sigmoidf(ag[i][0][e]) * ap[i][0][e];
.Lpeel_tail_21:
	ds_read_b128 v[176:179], v0
	ds_read_b128 v[180:183], v135 offset:18432
	ds_read_b128 v[184:187], v0 offset:4608
	s_add_i32 s7, s5, -1
	s_min_u32 s14, s7, s6
	s_lshl_b64 s[8:9], s[14:15], 7
	v_lshl_add_u64 v[144:145], v[122:123], 0, s[8:9]
	v_lshl_add_u64 v[148:149], v[124:125], 0, s[8:9]
	v_lshl_add_u64 v[152:153], v[126:127], 0, s[8:9]
	v_lshl_add_u64 v[156:157], v[128:129], 0, s[8:9]
	v_lshl_add_u64 v[160:161], v[130:131], 0, s[8:9]
	v_lshl_add_u64 v[164:165], v[132:133], 0, s[8:9]
	ds_read_b128 v[188:191], v0 offset:32
	ds_read_b128 v[192:195], v135 offset:18464
	ds_read_b128 v[196:199], v0 offset:4640
	s_waitcnt lgkmcnt(3)
	v_mfma_f32_32x32x16_bf16 v[50:65], v[176:179], v[180:183], v[50:65]
	v_mfma_f32_32x32x16_bf16 v[34:49], v[184:187], v[180:183], v[34:49]
	ds_read_b128 v[176:179], v0 offset:64
	ds_read_b128 v[180:183], v135 offset:18496
	ds_read_b128 v[184:187], v0 offset:4672
	s_waitcnt lgkmcnt(3)
	v_mfma_f32_32x32x16_bf16 v[50:65], v[188:191], v[192:195], v[50:65]
	v_mfma_f32_32x32x16_bf16 v[34:49], v[196:199], v[192:195], v[34:49]
	ds_read_b128 v[188:191], v0 offset:96
	ds_read_b128 v[192:195], v135 offset:18528
	ds_read_b128 v[196:199], v0 offset:4704
	s_waitcnt lgkmcnt(3)
	v_mfma_f32_32x32x16_bf16 v[50:65], v[176:179], v[180:183], v[50:65]
	s_waitcnt vmcnt(0)
	ds_write_b128 v134, v[66:69] offset:27648
	ds_write_b128 v136, v[70:73] offset:27648
	v_mfma_f32_32x32x16_bf16 v[34:49], v[184:187], v[180:183], v[34:49]
	ds_write_b128 v138, v[74:77] offset:27648
	s_waitcnt lgkmcnt(3)
	v_mfma_f32_32x32x16_bf16 v[50:65], v[188:191], v[192:195], v[50:65]
	ds_write_b128 v140, v[78:81] offset:27648
	ds_write_b128 v134, v[82:85] offset:46080
	v_mfma_f32_32x32x16_bf16 v[34:49], v[196:199], v[192:195], v[34:49]
	ds_write_b128 v136, v[86:89] offset:46080
	s_min_u32 s14, s5, s6
	s_lshl_b64 s[8:9], s[14:15], 7
	v_lshl_add_u64 v[66:67], v[122:123], 0, s[8:9]
	v_lshl_add_u64 v[70:71], v[124:125], 0, s[8:9]
	v_lshl_add_u64 v[74:75], v[126:127], 0, s[8:9]
	v_lshl_add_u64 v[78:79], v[128:129], 0, s[8:9]
	v_lshl_add_u64 v[82:83], v[130:131], 0, s[8:9]
	v_lshl_add_u64 v[86:87], v[132:133], 0, s[8:9]
	s_waitcnt lgkmcnt(0)
	s_barrier
	ds_read_b128 v[176:179], v0 offset:27648
	ds_read_b128 v[180:183], v135 offset:46080
	ds_read_b128 v[184:187], v0 offset:32256
	ds_read_b128 v[188:191], v0 offset:27680
	ds_read_b128 v[192:195], v135 offset:46112
	ds_read_b128 v[196:199], v0 offset:32288
	s_waitcnt lgkmcnt(3)
	v_mfma_f32_32x32x16_bf16 v[50:65], v[176:179], v[180:183], v[50:65]
	v_mfma_f32_32x32x16_bf16 v[34:49], v[184:187], v[180:183], v[34:49]
	ds_read_b128 v[176:179], v0 offset:27712
	ds_read_b128 v[180:183], v135 offset:46144
	ds_read_b128 v[184:187], v0 offset:32320
	s_waitcnt lgkmcnt(3)
	v_mfma_f32_32x32x16_bf16 v[50:65], v[188:191], v[192:195], v[50:65]
	v_mfma_f32_32x32x16_bf16 v[34:49], v[196:199], v[192:195], v[34:49]
	ds_read_b128 v[188:191], v0 offset:27744
	ds_read_b128 v[192:195], v135 offset:46176
	ds_read_b128 v[196:199], v0 offset:32352
	s_waitcnt lgkmcnt(3)
	v_mfma_f32_32x32x16_bf16 v[50:65], v[176:179], v[180:183], v[50:65]
	v_mfma_f32_32x32x16_bf16 v[34:49], v[184:187], v[180:183], v[34:49]
	s_waitcnt lgkmcnt(0)
	v_mfma_f32_32x32x16_bf16 v[50:65], v[188:191], v[192:195], v[50:65]
	v_mfma_f32_32x32x16_bf16 v[34:49], v[196:199], v[192:195], v[34:49]
	s_add_i32 s5, s5, 2
	s_cmp_lt_u32 s7, s4
	s_waitcnt lgkmcnt(0)
	s_barrier
	v_mul_f32_e32 v0, 0xbfb8aa3b, v18
	v_exp_f32_e32 v0, v0
	v_mul_f32_e32 v18, 0xbfb8aa3b, v19
	v_exp_f32_e32 v18, v18
	s_add_i32 s3, s3, 1
	v_add_f32_e32 v0, 1.0, v0
	s_cmp_lg_u32 s3, 3
	v_add_f32_e32 v19, 1.0, v18
	v_rcp_f32_e32 v18, v0
	v_mul_f32_e32 v0, 0xbfb8aa3b, v20
	v_exp_f32_e32 v0, v0
	v_mul_f32_e32 v20, 0xbfb8aa3b, v21
	v_rcp_f32_e32 v19, v19
	v_exp_f32_e32 v20, v20
	v_add_f32_e32 v0, 1.0, v0
	v_pk_fma_f32 v[120:121], v[18:19], v[50:51], v[120:121]
	v_rcp_f32_e32 v18, v0
	v_add_f32_e32 v0, 1.0, v20
	v_rcp_f32_e32 v19, v0
	v_mul_f32_e32 v0, 0xbfb8aa3b, v22
	v_exp_f32_e32 v0, v0
	v_mul_f32_e32 v20, 0xbfb8aa3b, v23
	v_exp_f32_e32 v20, v20
	v_pk_fma_f32 v[118:119], v[18:19], v[52:53], v[118:119]
	v_add_f32_e32 v0, 1.0, v0
	v_rcp_f32_e32 v18, v0
	v_add_f32_e32 v0, 1.0, v20
	v_rcp_f32_e32 v19, v0
	v_mul_f32_e32 v0, 0xbfb8aa3b, v24
	v_exp_f32_e32 v0, v0
	v_mul_f32_e32 v20, 0xbfb8aa3b, v25
	v_exp_f32_e32 v20, v20
	v_pk_fma_f32 v[116:117], v[18:19], v[54:55], v[116:117]
	v_add_f32_e32 v0, 1.0, v0
	v_rcp_f32_e32 v18, v0
	v_add_f32_e32 v0, 1.0, v20
	v_rcp_f32_e32 v19, v0
	v_mul_f32_e32 v0, 0xbfb8aa3b, v26
	v_exp_f32_e32 v0, v0
	v_mul_f32_e32 v20, 0xbfb8aa3b, v27
	v_exp_f32_e32 v20, v20
	v_pk_fma_f32 v[114:115], v[18:19], v[56:57], v[114:115]
	v_add_f32_e32 v0, 1.0, v0
	v_rcp_f32_e32 v18, v0
	v_add_f32_e32 v0, 1.0, v20
	v_rcp_f32_e32 v19, v0
	v_mul_f32_e32 v0, 0xbfb8aa3b, v28
	v_exp_f32_e32 v0, v0
	v_mul_f32_e32 v20, 0xbfb8aa3b, v29
	v_exp_f32_e32 v20, v20
	v_pk_fma_f32 v[112:113], v[18:19], v[58:59], v[112:113]
	v_add_f32_e32 v0, 1.0, v0
	v_rcp_f32_e32 v18, v0
	v_add_f32_e32 v0, 1.0, v20
	v_rcp_f32_e32 v19, v0
	v_mul_f32_e32 v0, 0xbfb8aa3b, v30
	v_exp_f32_e32 v0, v0
	v_mul_f32_e32 v20, 0xbfb8aa3b, v31
	v_exp_f32_e32 v20, v20
	v_pk_fma_f32 v[110:111], v[18:19], v[60:61], v[110:111]
	v_add_f32_e32 v0, 1.0, v0
	v_rcp_f32_e32 v18, v0
	v_add_f32_e32 v0, 1.0, v20
	v_rcp_f32_e32 v19, v0
	v_mul_f32_e32 v0, 0xbfb8aa3b, v32
	v_exp_f32_e32 v0, v0
	v_mul_f32_e32 v20, 0xbfb8aa3b, v33
	v_exp_f32_e32 v20, v20
	v_pk_fma_f32 v[108:109], v[18:19], v[62:63], v[108:109]
	v_add_f32_e32 v0, 1.0, v0
	v_rcp_f32_e32 v18, v0
	v_add_f32_e32 v0, 1.0, v20
	v_rcp_f32_e32 v19, v0
	v_mul_f32_e32 v0, 0xbfb8aa3b, v2
	v_exp_f32_e32 v0, v0
; DI float sigmoidf(float x) { return __builtin_amdgcn_rcpf(1.f + __expf(-x)); }
; DI void merge_tile(const Params& p, int mt, int nt, char* smem) {
;     ...
; #pragma unroll
;     for (int i = 0; i < 2; ++i)
; #pragma unroll
;       for (int e = 0; e < 16; ++e) mac[i][0][e] += sigmoidf(ag[i][0][e]) * ap[i][0][e];
;   }
;   float* Ct = (float*)smem;
;   acc_to_ct<1>(mac, Ct);
	v_mul_f32_e32 v2, 0xbfb8aa3b, v3
	v_exp_f32_e32 v3, v2
	v_pk_fma_f32 v[106:107], v[18:19], v[64:65], v[106:107]
	v_add_f32_e32 v0, 1.0, v0
	v_rcp_f32_e32 v2, v0
	v_add_f32_e32 v0, 1.0, v3
	v_rcp_f32_e32 v3, v0
	v_mul_f32_e32 v0, 0xbfb8aa3b, v4
	v_exp_f32_e32 v0, v0
	v_mul_f32_e32 v4, 0xbfb8aa3b, v5
	v_exp_f32_e32 v4, v4
	v_pk_fma_f32 v[104:105], v[2:3], v[34:35], v[104:105]
	v_add_f32_e32 v0, 1.0, v0
	v_rcp_f32_e32 v2, v0
	v_add_f32_e32 v0, 1.0, v4
	v_rcp_f32_e32 v3, v0
	v_mul_f32_e32 v0, 0xbfb8aa3b, v6
	v_exp_f32_e32 v0, v0
	v_mul_f32_e32 v4, 0xbfb8aa3b, v7
	v_exp_f32_e32 v4, v4
	v_pk_fma_f32 v[102:103], v[2:3], v[36:37], v[102:103]
	v_add_f32_e32 v0, 1.0, v0
	v_rcp_f32_e32 v2, v0
	v_add_f32_e32 v0, 1.0, v4
	v_rcp_f32_e32 v3, v0
	v_mul_f32_e32 v0, 0xbfb8aa3b, v8
	v_exp_f32_e32 v0, v0
	v_mul_f32_e32 v4, 0xbfb8aa3b, v9
	v_exp_f32_e32 v4, v4
	v_pk_fma_f32 v[100:101], v[2:3], v[38:39], v[100:101]
	v_add_f32_e32 v0, 1.0, v0
	v_rcp_f32_e32 v2, v0
	v_add_f32_e32 v0, 1.0, v4
	v_rcp_f32_e32 v3, v0
	v_mul_f32_e32 v0, 0xbfb8aa3b, v10
	v_exp_f32_e32 v0, v0
	v_mul_f32_e32 v4, 0xbfb8aa3b, v11
	v_exp_f32_e32 v4, v4
	v_pk_fma_f32 v[98:99], v[2:3], v[40:41], v[98:99]
	v_add_f32_e32 v0, 1.0, v0
	v_rcp_f32_e32 v2, v0
	v_add_f32_e32 v0, 1.0, v4
	v_rcp_f32_e32 v3, v0
	v_mul_f32_e32 v0, 0xbfb8aa3b, v12
	v_exp_f32_e32 v0, v0
	v_mul_f32_e32 v4, 0xbfb8aa3b, v13
	v_exp_f32_e32 v4, v4
	v_pk_fma_f32 v[96:97], v[2:3], v[42:43], v[96:97]
	v_add_f32_e32 v0, 1.0, v0
	v_rcp_f32_e32 v2, v0
	v_add_f32_e32 v0, 1.0, v4
	v_rcp_f32_e32 v3, v0
	v_mul_f32_e32 v0, 0xbfb8aa3b, v14
	v_exp_f32_e32 v0, v0
	v_mul_f32_e32 v4, 0xbfb8aa3b, v15
	v_exp_f32_e32 v4, v4
	v_pk_fma_f32 v[94:95], v[2:3], v[44:45], v[94:95]
	v_add_f32_e32 v0, 1.0, v0
	v_mul_f32_e32 v3, 0xbfb8aa3b, v16
	v_rcp_f32_e32 v2, v0
	v_add_f32_e32 v0, 1.0, v4
	v_exp_f32_e32 v4, v3
	v_mul_f32_e32 v3, 0xbfb8aa3b, v17
	v_exp_f32_e32 v5, v3
	v_rcp_f32_e32 v3, v0
	v_add_f32_e32 v0, 1.0, v4
	v_rcp_f32_e32 v4, v0
	v_add_f32_e32 v0, 1.0, v5
	v_rcp_f32_e32 v5, v0
	v_pk_fma_f32 v[92:93], v[2:3], v[46:47], v[92:93]
	v_pk_fma_f32 v[90:91], v[4:5], v[48:49], v[90:91]
	s_cbranch_scc1 .LBB0_18
	v_mov_b32_e32 v0, v230
	v_mov_b32_e32 v2, v230
	v_and_b32_e32 v3, 31, v0
	v_lshrrev_b32_e32 v0, 3, v0
	v_and_b32_e32 v0, 4, v0
	v_lshrrev_b32_e32 v4, 1, v2
	v_and_or_b32 v4, v4, s47, v0
	v_lshlrev_b32_e32 v0, 1, v2
	v_and_b32_e32 v0, 0x80, v0
	v_lshl_or_b32 v0, v3, 2, v0
	v_mad_u64_u32 v[2:3], s[4:5], v4, s79, v[0:1]
	v_add_u32_e32 v0, 0x400, v2
	ds_write2_b32 v0, v118, v119 offset0:8 offset1:140
	v_add_u32_e32 v0, 0x1000, v2
	ds_write2_b32 v0, v116, v117 offset0:32 offset1:164
	v_add_u32_e32 v0, 0x1400, v2
	ds_write2_b32 v0, v114, v115 offset0:40 offset1:172
	v_add_u32_e32 v0, 0x2000, v2
	ds_write2_b32 v0, v112, v113 offset0:64 offset1:196
	v_add_u32_e32 v0, 0x2400, v2
	ds_write2_b32 v0, v110, v111 offset0:72 offset1:204
	v_add_u32_e32 v0, 0x3000, v2
	ds_write2_b32 v0, v108, v109 offset0:96 offset1:228
	v_add_u32_e32 v0, 0x3400, v2
	ds_write2_b32 v0, v106, v107 offset0:104 offset1:236
	v_add_u32_e32 v0, 0x4200, v2
	ds_write2_b32 v0, v104, v105 offset1:132
	v_add_u32_e32 v0, 0x4600, v2
	ds_write2_b32 v0, v102, v103 offset0:8 offset1:140
	v_add_u32_e32 v0, 0x5200, v2
	ds_write2_b32 v0, v100, v101 offset0:32 offset1:164
	v_add_u32_e32 v0, 0x5600, v2
	ds_write2_b32 v0, v98, v99 offset0:40 offset1:172
	v_add_u32_e32 v0, 0x6200, v2
	ds_write2_b32 v0, v96, v97 offset0:64 offset1:196
	v_add_u32_e32 v0, 0x6600, v2
	ds_write2_b32 v0, v94, v95 offset0:72 offset1:204
	v_add_u32_e32 v0, 0x7200, v2
	ds_write2_b32 v0, v92, v93 offset0:96 offset1:228
	v_add_u32_e32 v0, 0x7600, v2
	ds_write2_b32 v0, v90, v91 offset0:104 offset1:236
	v_mov_b32_e32 v0, v230
	ds_write2_b32 v2, v120, v121 offset1:132
	s_waitcnt lgkmcnt(0)
	s_barrier
; #define TIDX (tid_launder())
; DI unsigned pack2(float a, float b) { hwf2 v = {a, b}; hwbf2 r = __builtin_convertvector(v, hwbf2); return __builtin_bit_cast(unsigned, r); }
; DI float siluf(float x) { return x * __builtin_amdgcn_rcpf(1.f + __expf(-x)); }
; DI void epi_store64(const float* Ct, int cb, const float* rn, int grp, const float* gain, bool silu, const float* bias,
;                     bf16_t* dst, size_t ldd, int dcol0, int m0, int Mmax) {
;   const int tid = TIDX, c = (tid & 15) * 4;
;   float4 gv = make_float4(1.f, 1.f, 1.f, 1.f), bv = make_float4(0.f, 0.f, 0.f, 0.f);
;   if (rn) gv = *(const float4*)(gain + c);
;   if (bias) bv = *(const float4*)(bias + c);
; #pragma unroll
;   for (int q = 0; q < 8; ++q) {
;     const int row = (tid >> 4) + 16 * q;
;     float4 v = *(const float4*)(Ct + row * 132 + cb + c);
;     v.x += bv.x; v.y += bv.y; v.z += bv.z; v.w += bv.w;
;     if (rn) { const float sc = rn[row * 2 + grp]; v.x *= sc * gv.x; v.y *= sc * gv.y; v.z *= sc * gv.z; v.w *= sc * gv.w; }
;     if (silu) { v.x = siluf(v.x); v.y = siluf(v.y); v.z = siluf(v.z); v.w = siluf(v.w); }
;     uint2 o; o.x = pack2(v.x, v.y); o.y = pack2(v.z, v.w);
;     *(uint2*)(dst + (size_t)(m0 + row) * ldd + dcol0 + c) = o;
;   }
	s_lshl_b32 s2, s2, 1
	v_lshlrev_b32_e32 v2, 2, v0
	v_ashrrev_i32_e32 v12, 4, v0
	v_and_b32_e32 v6, 60, v2
	v_mul_lo_u32 v0, v12, s79
	v_lshl_add_u32 v14, v6, 2, v0
	ds_read_b128 v[2:5], v14
	v_readlane_b32 s4, v250, 50
	v_lshlrev_b32_e32 v0, 1, v6
	ds_read_b128 v[6:9], v14 offset:8448
	v_readlane_b32 s5, v250, 51
	s_add_u32 s2, s4, s2
	v_add_u32_e32 v12, s1, v12
	s_addc_u32 s3, s5, 0
	s_waitcnt lgkmcnt(1)
	v_pk_add_f32 v[2:3], v[2:3], 0 op_sel_hi:[1,0]
	v_pk_add_f32 v[4:5], v[4:5], 0 op_sel_hi:[1,0]
	v_ashrrev_i32_e32 v13, 31, v12
	v_lshl_add_u64 v[10:11], s[2:3], 0, v[0:1]
	v_cvt_pk_bf16_f32 v2, v2, v3
	v_cvt_pk_bf16_f32 v3, v4, v5
	v_lshlrev_b64 v[4:5], 11, v[12:13]
	v_lshl_add_u64 v[4:5], v[10:11], 0, v[4:5]
	global_store_dwordx2 v[4:5], v[2:3], off
	s_waitcnt lgkmcnt(0)
	v_pk_add_f32 v[2:3], v[6:7], 0 op_sel_hi:[1,0]
	v_pk_add_f32 v[4:5], v[8:9], 0 op_sel_hi:[1,0]
	v_cvt_pk_bf16_f32 v6, v2, v3
	v_cvt_pk_bf16_f32 v7, v4, v5
	ds_read_b128 v[2:5], v14 offset:16896
	v_add_u32_e32 v8, 16, v12
	v_ashrrev_i32_e32 v9, 31, v8
	v_lshlrev_b64 v[8:9], 11, v[8:9]
	v_lshl_add_u64 v[8:9], v[10:11], 0, v[8:9]
	global_store_dwordx2 v[8:9], v[6:7], off
	ds_read_b128 v[6:9], v14 offset:25344
	s_waitcnt lgkmcnt(1)
	v_pk_add_f32 v[2:3], v[2:3], 0 op_sel_hi:[1,0]
	v_pk_add_f32 v[4:5], v[4:5], 0 op_sel_hi:[1,0]
	v_cvt_pk_bf16_f32 v2, v2, v3
	v_cvt_pk_bf16_f32 v3, v4, v5
	v_add_u32_e32 v4, 32, v12
	v_ashrrev_i32_e32 v5, 31, v4
	v_lshlrev_b64 v[4:5], 11, v[4:5]
	v_lshl_add_u64 v[4:5], v[10:11], 0, v[4:5]
	global_store_dwordx2 v[4:5], v[2:3], off
	s_waitcnt lgkmcnt(0)
	v_pk_add_f32 v[2:3], v[6:7], 0 op_sel_hi:[1,0]
	v_pk_add_f32 v[4:5], v[8:9], 0 op_sel_hi:[1,0]
	v_cvt_pk_bf16_f32 v6, v2, v3
	v_cvt_pk_bf16_f32 v7, v4, v5
	ds_read_b128 v[2:5], v14 offset:33792
	v_add_u32_e32 v8, 48, v12
	v_ashrrev_i32_e32 v9, 31, v8
	v_lshlrev_b64 v[8:9], 11, v[8:9]
	v_lshl_add_u64 v[8:9], v[10:11], 0, v[8:9]
	global_store_dwordx2 v[8:9], v[6:7], off
	ds_read_b128 v[6:9], v14 offset:42240
	s_waitcnt lgkmcnt(1)
	v_pk_add_f32 v[2:3], v[2:3], 0 op_sel_hi:[1,0]
	v_pk_add_f32 v[4:5], v[4:5], 0 op_sel_hi:[1,0]
	v_cvt_pk_bf16_f32 v2, v2, v3
	v_cvt_pk_bf16_f32 v3, v4, v5
	v_add_u32_e32 v4, 64, v12
	v_ashrrev_i32_e32 v5, 31, v4
	v_lshlrev_b64 v[4:5], 11, v[4:5]
	v_lshl_add_u64 v[4:5], v[10:11], 0, v[4:5]
	global_store_dwordx2 v[4:5], v[2:3], off
	s_waitcnt lgkmcnt(0)
	v_pk_add_f32 v[2:3], v[6:7], 0 op_sel_hi:[1,0]
	v_pk_add_f32 v[4:5], v[8:9], 0 op_sel_hi:[1,0]
	v_cvt_pk_bf16_f32 v6, v2, v3
	v_cvt_pk_bf16_f32 v7, v4, v5
	ds_read_b128 v[2:5], v14 offset:50688
	v_add_u32_e32 v8, 0x50, v12
	v_ashrrev_i32_e32 v9, 31, v8
	v_lshlrev_b64 v[8:9], 11, v[8:9]
	v_lshl_add_u64 v[8:9], v[10:11], 0, v[8:9]
	global_store_dwordx2 v[8:9], v[6:7], off
	ds_read_b128 v[6:9], v14 offset:59136
	s_waitcnt lgkmcnt(1)
	v_pk_add_f32 v[2:3], v[2:3], 0 op_sel_hi:[1,0]
	v_pk_add_f32 v[4:5], v[4:5], 0 op_sel_hi:[1,0]
	v_cvt_pk_bf16_f32 v2, v2, v3
	v_cvt_pk_bf16_f32 v3, v4, v5
	v_add_u32_e32 v4, 0x60, v12
	v_ashrrev_i32_e32 v5, 31, v4
	v_lshlrev_b64 v[4:5], 11, v[4:5]
	v_lshl_add_u64 v[4:5], v[10:11], 0, v[4:5]
	global_store_dwordx2 v[4:5], v[2:3], off
	s_waitcnt lgkmcnt(0)
	v_pk_add_f32 v[2:3], v[6:7], 0 op_sel_hi:[1,0]
	v_pk_add_f32 v[4:5], v[8:9], 0 op_sel_hi:[1,0]
	v_cvt_pk_bf16_f32 v2, v2, v3
	v_cvt_pk_bf16_f32 v3, v4, v5
	v_add_u32_e32 v4, 0x70, v12
	v_ashrrev_i32_e32 v5, 31, v4
	v_readlane_b32 s1, v250, 60
	v_lshlrev_b64 v[4:5], 11, v[4:5]
	s_add_i32 s0, s0, s1
	v_lshl_add_u64 v[4:5], v[10:11], 0, v[4:5]
	s_cmpk_gt_u32 s0, 0x1ff
	v_readlane_b32 s6, v250, 52
	v_readlane_b32 s7, v250, 53
	global_store_dwordx2 v[4:5], v[2:3], off
	s_barrier
	s_cbranch_scc0 .LBB0_17

; #define G_STORE(ST, S, unused) do { char* d_ = smem + (ST) * STAGE; \
;     *(uint4*)(d_ + alo[0]) = S##a0; *(uint4*)(d_ + alo[1]) = S##a1; *(uint4*)(d_ + alo[2]) = S##a2; *(uint4*)(d_ + alo[3]) = S##a3; \
;     *(uint4*)(d_ + blo[0]) = S##b0; *(uint4*)(d_ + blo[1]) = S##b1; \
;     if (NBCH == 4) { *(uint4*)(d_ + blo[NBCH - 2]) = S##b2; *(uint4*)(d_ + blo[NBCH - 1]) = S##b3; } } while (0)
; template <int NJ, class RowA>
; DI void gemm_main(f32x16 (&acc)[2][NJ], const bf16_t* __restrict__ A, RowA rowA, size_t kstrideA, int m0, int Mmax,
;                   const bf16_t* __restrict__ Bt, size_t ldb, int n0, int nk, char* smem) {
;     ...
;   __syncthreads();
;   G_LOAD(x0, 0, 0);
;   G_LOAD(x1, 0, 1);
;   G_STORE(0, x0, 0);
;   __syncthreads();
; #pragma unroll 1
;   for (int kt = 0; kt < nk; kt += 2) {
;     G_LOAD(x0, 0, (kt + 2 < nk ? kt + 2 : nk - 1));
;     G_COMPUTE(0);
;     G_STORE(1, x1, 0);
;     __syncthreads();
;     G_LOAD(x1, 0, (kt + 3 < nk ? kt + 3 : nk - 1));
;     G_COMPUTE(1);
;     G_STORE(0, x0, 0);
;     __syncthreads();
.LBB0_1956:
	s_cmp_lt_i32 s0, 12
	s_cbranch_scc0 .Lpeel_tail_1956
	ds_read_b128 v[166:169], v0
	ds_read_b128 v[170:173], v139 offset:18432
	ds_read_b128 v[174:177], v139 offset:23040
	ds_read_b128 v[178:181], v0 offset:4608
	s_add_i32 s1, s0, 4
	s_min_u32 s1, s1, 15
	s_lshl_b32 s14, s1, 7
	v_lshl_add_u64 v[98:99], v[122:123], 0, s[14:15]
	v_lshl_add_u64 v[102:103], v[124:125], 0, s[14:15]
	v_lshl_add_u64 v[106:107], v[126:127], 0, s[14:15]
	v_lshl_add_u64 v[110:111], v[128:129], 0, s[14:15]
	v_lshl_add_u64 v[114:115], v[130:131], 0, s[14:15]
	v_lshl_add_u64 v[118:119], v[132:133], 0, s[14:15]
	s_add_i32 s0, s0, 2
	v_lshl_add_u64 v[158:159], v[134:135], 0, s[14:15]
	v_lshl_add_u64 v[160:161], v[136:137], 0, s[14:15]
	ds_read_b128 v[182:185], v0 offset:32
	ds_read_b128 v[186:189], v139 offset:18464
	ds_read_b128 v[190:193], v139 offset:23072
	ds_read_b128 v[194:197], v0 offset:4640
	s_waitcnt lgkmcnt(4)
	v_mfma_f32_32x32x16_bf16 v[50:65], v[166:169], v[170:173], v[50:65]
	global_load_dwordx4 v[98:101], v[98:99], off
	v_mfma_f32_32x32x16_bf16 v[34:49], v[166:169], v[174:177], v[34:49]
	global_load_dwordx4 v[102:105], v[102:103], off
	v_mfma_f32_32x32x16_bf16 v[18:33], v[178:181], v[170:173], v[18:33]
	global_load_dwordx4 v[106:109], v[106:107], off
	v_mfma_f32_32x32x16_bf16 v[2:17], v[178:181], v[174:177], v[2:17]
	global_load_dwordx4 v[110:113], v[110:111], off
	ds_read_b128 v[166:169], v0 offset:64
	ds_read_b128 v[170:173], v139 offset:18496
	ds_read_b128 v[174:177], v139 offset:23104
	ds_read_b128 v[178:181], v0 offset:4672
	s_waitcnt lgkmcnt(4)
	v_mfma_f32_32x32x16_bf16 v[50:65], v[182:185], v[186:189], v[50:65]
	global_load_dwordx4 v[114:117], v[114:115], off
	v_mfma_f32_32x32x16_bf16 v[34:49], v[182:185], v[190:193], v[34:49]
	global_load_dwordx4 v[118:121], v[118:119], off
	v_mfma_f32_32x32x16_bf16 v[18:33], v[194:197], v[186:189], v[18:33]
	global_load_dwordx4 v[146:149], v[160:161], off
	v_mfma_f32_32x32x16_bf16 v[2:17], v[194:197], v[190:193], v[2:17]
	global_load_dwordx4 v[150:153], v[158:159], off
	ds_read_b128 v[182:185], v0 offset:96
	ds_read_b128 v[186:189], v139 offset:18528
	ds_read_b128 v[190:193], v139 offset:23136
	ds_read_b128 v[194:197], v0 offset:4704
	s_waitcnt lgkmcnt(4)
	v_mfma_f32_32x32x16_bf16 v[50:65], v[166:169], v[170:173], v[50:65]
	s_waitcnt vmcnt(8)
	ds_write_b128 v138, v[74:77] offset:36864
	v_mfma_f32_32x32x16_bf16 v[34:49], v[166:169], v[174:177], v[34:49]
	ds_write_b128 v140, v[78:81] offset:36864
	v_mfma_f32_32x32x16_bf16 v[18:33], v[178:181], v[170:173], v[18:33]
	ds_write_b128 v142, v[82:85] offset:36864
	v_mfma_f32_32x32x16_bf16 v[2:17], v[178:181], v[174:177], v[2:17]
	ds_write_b128 v144, v[86:89] offset:36864
	s_waitcnt lgkmcnt(4)
	v_mfma_f32_32x32x16_bf16 v[50:65], v[182:185], v[186:189], v[50:65]
	ds_write_b128 v138, v[90:93] offset:55296
	v_mfma_f32_32x32x16_bf16 v[34:49], v[182:185], v[190:193], v[34:49]
	ds_write_b128 v140, v[94:97] offset:55296
	v_mfma_f32_32x32x16_bf16 v[18:33], v[194:197], v[186:189], v[18:33]
	ds_write_b128 v142, v[66:69] offset:55296
	v_mfma_f32_32x32x16_bf16 v[2:17], v[194:197], v[190:193], v[2:17]
	ds_write_b128 v144, v[70:73] offset:55296
	s_min_u32 s1, s0, 12
	s_lshl_b32 s14, s1, 7
	v_lshl_add_u64 v[66:67], v[122:123], 0, s[14:15]
	v_lshl_add_u64 v[68:69], v[124:125], 0, s[14:15]
	v_lshl_add_u64 v[70:71], v[126:127], 0, s[14:15]
	v_lshl_add_u64 v[72:73], v[128:129], 0, s[14:15]
	v_lshl_add_u64 v[90:91], v[130:131], 0, s[14:15]
	v_lshl_add_u64 v[94:95], v[132:133], 0, s[14:15]
	s_waitcnt lgkmcnt(0)
	s_barrier
	ds_read_b128 v[166:169], v0 offset:36864
	ds_read_b128 v[170:173], v139 offset:55296
	ds_read_b128 v[174:177], v139 offset:59904
	ds_read_b128 v[178:181], v0 offset:41472
	v_lshl_add_u64 v[154:155], v[134:135], 0, s[14:15]
	v_lshl_add_u64 v[156:157], v[136:137], 0, s[14:15]
	ds_read_b128 v[182:185], v0 offset:36896
	ds_read_b128 v[186:189], v139 offset:55328
	ds_read_b128 v[190:193], v139 offset:59936
	ds_read_b128 v[194:197], v0 offset:41504
	s_waitcnt lgkmcnt(4)
	v_mfma_f32_32x32x16_bf16 v[50:65], v[166:169], v[170:173], v[50:65]
	global_load_dwordx4 v[74:77], v[66:67], off offset:384
	v_mfma_f32_32x32x16_bf16 v[34:49], v[166:169], v[174:177], v[34:49]
	global_load_dwordx4 v[78:81], v[68:69], off offset:384
	v_mfma_f32_32x32x16_bf16 v[18:33], v[178:181], v[170:173], v[18:33]
	global_load_dwordx4 v[82:85], v[70:71], off offset:384
	v_mfma_f32_32x32x16_bf16 v[2:17], v[178:181], v[174:177], v[2:17]
	global_load_dwordx4 v[86:89], v[72:73], off offset:384
	ds_read_b128 v[166:169], v0 offset:36928
	ds_read_b128 v[170:173], v139 offset:55360
	ds_read_b128 v[174:177], v139 offset:59968
	ds_read_b128 v[178:181], v0 offset:41536
	s_waitcnt lgkmcnt(4)
	v_mfma_f32_32x32x16_bf16 v[50:65], v[182:185], v[186:189], v[50:65]
	global_load_dwordx4 v[90:93], v[90:91], off offset:384
	v_mfma_f32_32x32x16_bf16 v[34:49], v[182:185], v[190:193], v[34:49]
	global_load_dwordx4 v[94:97], v[94:95], off offset:384
	v_mfma_f32_32x32x16_bf16 v[18:33], v[194:197], v[186:189], v[18:33]
	global_load_dwordx4 v[66:69], v[154:155], off offset:384
	v_mfma_f32_32x32x16_bf16 v[2:17], v[194:197], v[190:193], v[2:17]
	global_load_dwordx4 v[70:73], v[156:157], off offset:384
	ds_read_b128 v[182:185], v0 offset:36960
	ds_read_b128 v[186:189], v139 offset:55392
	ds_read_b128 v[190:193], v139 offset:60000
	ds_read_b128 v[194:197], v0 offset:41568
	s_waitcnt lgkmcnt(4)
	v_mfma_f32_32x32x16_bf16 v[50:65], v[166:169], v[170:173], v[50:65]
	s_waitcnt vmcnt(8)
	ds_write_b128 v138, v[98:101]
	v_mfma_f32_32x32x16_bf16 v[34:49], v[166:169], v[174:177], v[34:49]
	ds_write_b128 v140, v[102:105]
	v_mfma_f32_32x32x16_bf16 v[18:33], v[178:181], v[170:173], v[18:33]
	ds_write_b128 v142, v[106:109]
	v_mfma_f32_32x32x16_bf16 v[2:17], v[178:181], v[174:177], v[2:17]
	ds_write_b128 v144, v[110:113]
	s_waitcnt lgkmcnt(4)
	v_mfma_f32_32x32x16_bf16 v[50:65], v[182:185], v[186:189], v[50:65]
	ds_write_b128 v138, v[114:117] offset:18432
	v_mfma_f32_32x32x16_bf16 v[34:49], v[182:185], v[190:193], v[34:49]
	ds_write_b128 v140, v[118:121] offset:18432
	v_mfma_f32_32x32x16_bf16 v[18:33], v[194:197], v[186:189], v[18:33]
	ds_write_b128 v142, v[150:153] offset:18432
	v_mfma_f32_32x32x16_bf16 v[2:17], v[194:197], v[190:193], v[2:17]
	ds_write_b128 v144, v[146:149] offset:18432
	s_cmp_lt_u32 s0, 14
	s_waitcnt lgkmcnt(0)
	s_barrier
	s_branch .LBB0_1956
; #define G_STORE(ST, S, unused) do { char* d_ = smem + (ST) * STAGE; \
;     *(uint4*)(d_ + alo[0]) = S##a0; *(uint4*)(d_ + alo[1]) = S##a1; *(uint4*)(d_ + alo[2]) = S##a2; *(uint4*)(d_ + alo[3]) = S##a3; \
;     *(uint4*)(d_ + blo[0]) = S##b0; *(uint4*)(d_ + blo[1]) = S##b1; \
;     if (NBCH == 4) { *(uint4*)(d_ + blo[NBCH - 2]) = S##b2; *(uint4*)(d_ + blo[NBCH - 1]) = S##b3; } } while (0)
; template <int NJ, class RowA>
; DI void gemm_main(f32x16 (&acc)[2][NJ], const bf16_t* __restrict__ A, RowA rowA, size_t kstrideA, int m0, int Mmax,
;                   const bf16_t* __restrict__ Bt, size_t ldb, int n0, int nk, char* smem) {
;     ...
;   __syncthreads();
;   G_LOAD(x0, 0, 0);
;   G_LOAD(x1, 0, 1);
;   G_STORE(0, x0, 0);
;   __syncthreads();
; #pragma unroll 1
;   for (int kt = 0; kt < nk; kt += 2) {
;     G_LOAD(x0, 0, (kt + 2 < nk ? kt + 2 : nk - 1));
;     G_COMPUTE(0);
;     G_STORE(1, x1, 0);
;     __syncthreads();
;     G_LOAD(x1, 0, (kt + 3 < nk ? kt + 3 : nk - 1));
;     G_COMPUTE(1);
;     G_STORE(0, x0, 0);
;     __syncthreads();
.Lpeel_tail_1956:
	ds_read_b128 v[166:169], v0
	ds_read_b128 v[170:173], v139 offset:18432
	ds_read_b128 v[174:177], v139 offset:23040
	ds_read_b128 v[178:181], v0 offset:4608
	s_add_i32 s1, s0, 4
	s_min_u32 s1, s1, 15
	s_lshl_b32 s14, s1, 7
	v_lshl_add_u64 v[98:99], v[122:123], 0, s[14:15]
	v_lshl_add_u64 v[102:103], v[124:125], 0, s[14:15]
	v_lshl_add_u64 v[106:107], v[126:127], 0, s[14:15]
	v_lshl_add_u64 v[110:111], v[128:129], 0, s[14:15]
	v_lshl_add_u64 v[114:115], v[130:131], 0, s[14:15]
	v_lshl_add_u64 v[118:119], v[132:133], 0, s[14:15]
	s_add_i32 s0, s0, 2
	v_lshl_add_u64 v[158:159], v[134:135], 0, s[14:15]
	v_lshl_add_u64 v[160:161], v[136:137], 0, s[14:15]
	ds_read_b128 v[182:185], v0 offset:32
	ds_read_b128 v[186:189], v139 offset:18464
	ds_read_b128 v[190:193], v139 offset:23072
	ds_read_b128 v[194:197], v0 offset:4640
	s_waitcnt lgkmcnt(4)
	v_mfma_f32_32x32x16_bf16 v[50:65], v[166:169], v[170:173], v[50:65]
	v_mfma_f32_32x32x16_bf16 v[34:49], v[166:169], v[174:177], v[34:49]
	v_mfma_f32_32x32x16_bf16 v[18:33], v[178:181], v[170:173], v[18:33]
	v_mfma_f32_32x32x16_bf16 v[2:17], v[178:181], v[174:177], v[2:17]
	ds_read_b128 v[166:169], v0 offset:64
	ds_read_b128 v[170:173], v139 offset:18496
	ds_read_b128 v[174:177], v139 offset:23104
	ds_read_b128 v[178:181], v0 offset:4672
	s_waitcnt lgkmcnt(4)
	v_mfma_f32_32x32x16_bf16 v[50:65], v[182:185], v[186:189], v[50:65]
	v_mfma_f32_32x32x16_bf16 v[34:49], v[182:185], v[190:193], v[34:49]
	v_mfma_f32_32x32x16_bf16 v[18:33], v[194:197], v[186:189], v[18:33]
	v_mfma_f32_32x32x16_bf16 v[2:17], v[194:197], v[190:193], v[2:17]
	ds_read_b128 v[182:185], v0 offset:96
	ds_read_b128 v[186:189], v139 offset:18528
	ds_read_b128 v[190:193], v139 offset:23136
	ds_read_b128 v[194:197], v0 offset:4704
	s_waitcnt lgkmcnt(4)
	v_mfma_f32_32x32x16_bf16 v[50:65], v[166:169], v[170:173], v[50:65]
	s_waitcnt vmcnt(0)
	ds_write_b128 v138, v[74:77] offset:36864
	v_mfma_f32_32x32x16_bf16 v[34:49], v[166:169], v[174:177], v[34:49]
	ds_write_b128 v140, v[78:81] offset:36864
	v_mfma_f32_32x32x16_bf16 v[18:33], v[178:181], v[170:173], v[18:33]
	ds_write_b128 v142, v[82:85] offset:36864
	v_mfma_f32_32x32x16_bf16 v[2:17], v[178:181], v[174:177], v[2:17]
	ds_write_b128 v144, v[86:89] offset:36864
	s_waitcnt lgkmcnt(4)
	v_mfma_f32_32x32x16_bf16 v[50:65], v[182:185], v[186:189], v[50:65]
	ds_write_b128 v138, v[90:93] offset:55296
	v_mfma_f32_32x32x16_bf16 v[34:49], v[182:185], v[190:193], v[34:49]
	ds_write_b128 v140, v[94:97] offset:55296
	v_mfma_f32_32x32x16_bf16 v[18:33], v[194:197], v[186:189], v[18:33]
	ds_write_b128 v142, v[66:69] offset:55296
	v_mfma_f32_32x32x16_bf16 v[2:17], v[194:197], v[190:193], v[2:17]
	ds_write_b128 v144, v[70:73] offset:55296
	s_min_u32 s1, s0, 12
	s_lshl_b32 s14, s1, 7
	v_lshl_add_u64 v[66:67], v[122:123], 0, s[14:15]
	v_lshl_add_u64 v[68:69], v[124:125], 0, s[14:15]
	v_lshl_add_u64 v[70:71], v[126:127], 0, s[14:15]
	v_lshl_add_u64 v[72:73], v[128:129], 0, s[14:15]
	v_lshl_add_u64 v[90:91], v[130:131], 0, s[14:15]
	v_lshl_add_u64 v[94:95], v[132:133], 0, s[14:15]
	s_waitcnt lgkmcnt(0)
	s_barrier
	ds_read_b128 v[166:169], v0 offset:36864
	ds_read_b128 v[170:173], v139 offset:55296
	ds_read_b128 v[174:177], v139 offset:59904
	ds_read_b128 v[178:181], v0 offset:41472
	v_lshl_add_u64 v[154:155], v[134:135], 0, s[14:15]
	v_lshl_add_u64 v[156:157], v[136:137], 0, s[14:15]
	ds_read_b128 v[182:185], v0 offset:36896
	ds_read_b128 v[186:189], v139 offset:55328
	ds_read_b128 v[190:193], v139 offset:59936
	ds_read_b128 v[194:197], v0 offset:41504
	s_waitcnt lgkmcnt(4)
	v_mfma_f32_32x32x16_bf16 v[50:65], v[166:169], v[170:173], v[50:65]
	v_mfma_f32_32x32x16_bf16 v[34:49], v[166:169], v[174:177], v[34:49]
	v_mfma_f32_32x32x16_bf16 v[18:33], v[178:181], v[170:173], v[18:33]
	v_mfma_f32_32x32x16_bf16 v[2:17], v[178:181], v[174:177], v[2:17]
	ds_read_b128 v[166:169], v0 offset:36928
	ds_read_b128 v[170:173], v139 offset:55360
	ds_read_b128 v[174:177], v139 offset:59968
	ds_read_b128 v[178:181], v0 offset:41536
	s_waitcnt lgkmcnt(4)
	v_mfma_f32_32x32x16_bf16 v[50:65], v[182:185], v[186:189], v[50:65]
	v_mfma_f32_32x32x16_bf16 v[34:49], v[182:185], v[190:193], v[34:49]
	v_mfma_f32_32x32x16_bf16 v[18:33], v[194:197], v[186:189], v[18:33]
	v_mfma_f32_32x32x16_bf16 v[2:17], v[194:197], v[190:193], v[2:17]
	ds_read_b128 v[182:185], v0 offset:36960
	ds_read_b128 v[186:189], v139 offset:55392
	ds_read_b128 v[190:193], v139 offset:60000
	ds_read_b128 v[194:197], v0 offset:41568
	s_waitcnt lgkmcnt(4)
	v_mfma_f32_32x32x16_bf16 v[50:65], v[166:169], v[170:173], v[50:65]
	v_mfma_f32_32x32x16_bf16 v[34:49], v[166:169], v[174:177], v[34:49]
	v_mfma_f32_32x32x16_bf16 v[18:33], v[178:181], v[170:173], v[18:33]
	v_mfma_f32_32x32x16_bf16 v[2:17], v[178:181], v[174:177], v[2:17]
	s_waitcnt lgkmcnt(0)
	v_mfma_f32_32x32x16_bf16 v[50:65], v[182:185], v[186:189], v[50:65]
	v_mfma_f32_32x32x16_bf16 v[34:49], v[182:185], v[190:193], v[34:49]
	v_mfma_f32_32x32x16_bf16 v[18:33], v[194:197], v[186:189], v[18:33]
	v_mfma_f32_32x32x16_bf16 v[2:17], v[194:197], v[190:193], v[2:17]
	s_cmp_lt_u32 s0, 14
	s_waitcnt lgkmcnt(0)
	s_barrier
; #define TIDX (tid_launder())
; DI void inproj_tile(const Params& p, int l, int mt, int tn, char* smem) {
;     ...
;   if (tn <= 3) {
;     epi_rownorm(Ct, rn, 64);
;     const float* g = tn < 2 ? p.a_q_norm + l * 64 : p.c_q_norm + l * 64;
;     epi_store64(Ct, 0, rn, 0, g, false, nullptr, p.projA, LDA_A, tn * 128, m0, T_TOK);
;     epi_store64(Ct, 64, rn, 1, g, false, nullptr, p.projA, LDA_A, tn * 128 + 64, m0, T_TOK);
;   } else if (tn == 4) {
;     epi_rownorm(Ct, rn, 128);
;     const float* g = p.a_kv_norm + l * 128;
;     epi_store64(Ct, 0, rn, 0, g, false, nullptr, p.projA, LDA_A, 512, m0, T_TOK);
;     epi_store64(Ct, 64, rn, 1, g + 64, false, nullptr, p.projA, LDA_A, 576, m0, T_TOK);
;   } else if (tn <= 8) {
;     epi_store64(Ct, 0, nullptr, 0, nullptr, false, nullptr, p.projA, LDA_A, tn * 128, m0, T_TOK);
;     epi_store64(Ct, 64, nullptr, 0, nullptr, false, nullptr, p.projA, LDA_A, tn * 128 + 64, m0, T_TOK);
;   } else if (tn == 9) {
;     epi_storeKF(Ct, 0, nullptr, 0, nullptr, p.kidxF + ((size_t)b * 64 + s0 / 32) * 2048);
;     epi_store64(Ct, 64, nullptr, 0, nullptr, false, nullptr, p.projA, LDA_A, tn * 128 + 64, m0, T_TOK);
;   } else if (tn == 10) {
;     epi_rownorm(Ct, rn, 64);
;     epi_store64(Ct, 0, nullptr, 0, nullptr, false, nullptr, p.projA, LDA_A, 1280, m0, T_TOK);
;     epi_storeKF(Ct, 64, rn, 1, p.c_k_norm + (l * 3 + 1) * 64, p.kselF + ((size_t)b * 64 + s0 / 32) * 2048);
;   } else if (tn == 11) {
;     epi_rownorm(Ct, rn, 64);
;     epi_storeKF(Ct, 0, rn, 0, p.c_k_norm + (l * 3 + 2) * 64, p.kwinF + ((size_t)b * 64 + s0 / 32) * 2048);
;     epi_storeVF(Ct, 64, p.vselT + ((size_t)b * 64 + s0 / 32) * 2048);
;   } else if (tn == 12) {
;     epi_storeVF(Ct, 0, p.vwinT + ((size_t)b * 64 + s0 / 32) * 2048);
;     for (int idx = TIDX; idx < 128 * 32; idx += 256) {
;       const int row = idx >> 5, c = idx & 31;
;       p.small[(size_t)(m0 + row) * 32 + c] = Ct[row * 132 + 64 + c];
;     }
;   } else if (tn <= 24) {
;     const int c0 = (tn - 13) * 128;
;     epi_store64(Ct, 0, nullptr, 0, nullptr, false, nullptr, p.projB, LDA_B, c0, m0, T_TOK);
;     epi_store64(Ct, 64, nullptr, 0, nullptr, false, nullptr, p.projB, LDA_B, c0 + 64, m0, T_TOK);
;   } else {
;     const int c0 = (tn - 25) * 128;
;     epi_store64(Ct, 0, nullptr, 0, nullptr, true, nullptr, p.projZ, LDA_Z, c0, m0, T_TOK);
	v_mov_b32_e32 v0, v230
	s_waitcnt vmcnt(1)
	v_mov_b32_e32 v66, v230
	v_and_b32_e32 v67, 31, v0
	v_lshrrev_b32_e32 v0, 3, v0
	v_and_b32_e32 v0, 4, v0
	v_lshrrev_b32_e32 v68, 1, v66
	v_and_or_b32 v0, v68, s47, v0
	v_and_or_b32 v66, v66, 64, v67
	v_mul_lo_u32 v0, v0, s79
	v_lshl_add_u32 v0, v66, 2, v0
	ds_write2_b32 v0, v50, v34 offset1:32
	ds_write2_b32 v0, v51, v35 offset0:132 offset1:164
	v_add_u32_e32 v34, 0x400, v0
	ds_write2_b32 v34, v52, v36 offset0:8 offset1:40
	ds_write2_b32 v34, v53, v37 offset0:140 offset1:172
	v_add_u32_e32 v34, 0x1000, v0
	ds_write2_b32 v34, v54, v38 offset0:32 offset1:64
	ds_write2_b32 v34, v55, v39 offset0:164 offset1:196
	v_add_u32_e32 v34, 0x1400, v0
	ds_write2_b32 v34, v56, v40 offset0:40 offset1:72
	ds_write2_b32 v34, v57, v41 offset0:172 offset1:204
	v_add_u32_e32 v34, 0x2000, v0
	ds_write2_b32 v34, v58, v42 offset0:64 offset1:96
	ds_write2_b32 v34, v59, v43 offset0:196 offset1:228
	v_add_u32_e32 v34, 0x2400, v0
	ds_write2_b32 v34, v60, v44 offset0:72 offset1:104
	ds_write2_b32 v34, v61, v45 offset0:204 offset1:236
	v_add_u32_e32 v34, 0x3000, v0
	ds_write2_b32 v34, v62, v46 offset0:96 offset1:128
	v_add_u32_e32 v34, 0x3200, v0
	ds_write2_b32 v34, v63, v47 offset0:100 offset1:132
	v_add_u32_e32 v34, 0x3400, v0
	ds_write2_b32 v34, v64, v48 offset0:104 offset1:136
	v_add_u32_e32 v34, 0x3600, v0
	ds_write2_b32 v34, v65, v49 offset0:108 offset1:140
	v_add_u32_e32 v34, 0x4000, v0
	ds_write2_b32 v34, v18, v2 offset0:128 offset1:160
	v_add_u32_e32 v2, 0x4400, v0
	ds_write2_b32 v2, v19, v3 offset0:4 offset1:36
	ds_write2_b32 v2, v20, v4 offset0:136 offset1:168
	v_add_u32_e32 v2, 0x4800, v0
	ds_write2_b32 v2, v21, v5 offset0:12 offset1:44
	v_add_u32_e32 v2, 0x5000, v0
	ds_write2_b32 v2, v22, v6 offset0:160 offset1:192
	v_add_u32_e32 v2, 0x5400, v0
	ds_write2_b32 v2, v23, v7 offset0:36 offset1:68
	ds_write2_b32 v2, v24, v8 offset0:168 offset1:200
	v_add_u32_e32 v2, 0x5800, v0
	ds_write2_b32 v2, v25, v9 offset0:44 offset1:76
	v_add_u32_e32 v2, 0x6000, v0
	ds_write2_b32 v2, v26, v10 offset0:192 offset1:224
	v_add_u32_e32 v2, 0x6400, v0
	ds_write2_b32 v2, v27, v11 offset0:68 offset1:100
	ds_write2_b32 v2, v28, v12 offset0:200 offset1:232
	v_add_u32_e32 v2, 0x6800, v0
	ds_write2_b32 v2, v29, v13 offset0:76 offset1:108
	v_add_u32_e32 v2, 0x7200, v0
	ds_write2_b32 v2, v30, v14 offset0:96 offset1:128
	v_add_u32_e32 v2, 0x7400, v0
	ds_write2_b32 v2, v31, v15 offset0:100 offset1:132
	v_add_u32_e32 v2, 0x7600, v0
	v_add_u32_e32 v0, 0x7800, v0
	s_cmp_gt_i32 s12, 3
	s_mov_b64 s[0:1], -1
	ds_write2_b32 v2, v32, v16 offset0:104 offset1:136
	ds_write2_b32 v0, v33, v17 offset0:108 offset1:140
	s_waitcnt lgkmcnt(0)
	s_barrier
	s_cbranch_scc0 .LBB0_2086
	s_cmp_lg_u32 s12, 4
	s_cbranch_scc0 .LBB0_2045
	s_cmp_gt_u32 s12, 8
	s_cbranch_scc0 .LBB0_2042
	s_ashr_i32 s0, s3, 7
	s_add_i32 s4, s0, s4
	s_ashr_i32 s0, s11, 31
	s_lshr_b32 s0, s0, 21
	s_add_i32 s0, s11, s0
	s_and_b32 s0, s0, 0xfffff800
	s_sub_i32 s13, s11, s0
	s_cmp_lt_i32 s12, 11
	s_mov_b64 s[0:1], -1
	s_cbranch_scc1 .LBB0_2012
	s_cmp_lt_i32 s12, 12
	s_cbranch_scc1 .LBB0_1982
	s_cmp_lg_u32 s12, 12
	s_cbranch_scc0 .LBB0_1968
	s_cmp_gt_u32 s12, 24
	s_mov_b32 s3, s15
	s_cbranch_scc0 .LBB0_1965
	v_mov_b32_e32 v0, v230
	v_readlane_b32 s16, v252, 57
	s_lshl_b64 s[0:1], s[2:3], 1
	v_lshlrev_b32_e32 v2, 2, v0
	v_readlane_b32 s28, v253, 5
	v_and_b32_e32 v4, 60, v2
	v_readlane_b32 s29, v253, 6
	s_add_u32 s0, s28, s0
	v_ashrrev_i32_e32 v10, 4, v0
	s_addc_u32 s1, s29, s1
	v_lshlrev_b32_e32 v0, 1, v4
	v_lshl_add_u64 v[2:3], s[0:1], 0, v[0:1]
	v_mul_lo_u32 v0, v10, s79
	v_lshl_add_u32 v0, v4, 2, v0
	ds_read_b128 v[4:7], v0
	s_movk_i32 s6, 0xe700
	s_mov_b32 s7, -1
	v_lshl_add_u64 v[2:3], v[2:3], 0, s[6:7]
	v_readlane_b32 s17, v252, 58
	s_waitcnt lgkmcnt(0)
	v_pk_add_f32 v[4:5], v[4:5], 0 op_sel_hi:[1,0]
	v_pk_add_f32 v[6:7], v[6:7], 0 op_sel_hi:[1,0]
	v_mul_f32_e32 v8, 0xbfb8aa3b, v4
	v_mul_f32_e32 v9, 0xbfb8aa3b, v5
	v_exp_f32_e32 v8, v8
	v_exp_f32_e32 v9, v9
	v_readlane_b32 s18, v252, 59
	v_readlane_b32 s19, v252, 60
	v_add_f32_e32 v8, 1.0, v8
	v_add_f32_e32 v9, 1.0, v9
	v_rcp_f32_e32 v8, v8
	v_rcp_f32_e32 v9, v9
	v_readlane_b32 s20, v252, 61
	v_readlane_b32 s21, v252, 62
	v_readlane_b32 s22, v252, 63
	v_pk_mul_f32 v[4:5], v[4:5], v[8:9]
	v_mul_f32_e32 v8, 0xbfb8aa3b, v6
	v_mul_f32_e32 v9, 0xbfb8aa3b, v7
	v_exp_f32_e32 v8, v8
	v_exp_f32_e32 v9, v9
	v_readlane_b32 s23, v253, 0
	v_readlane_b32 s24, v253, 1
	v_add_f32_e32 v8, 1.0, v8
	v_add_f32_e32 v9, 1.0, v9
	v_rcp_f32_e32 v8, v8
	v_rcp_f32_e32 v9, v9
	v_readlane_b32 s25, v253, 2
	v_readlane_b32 s26, v253, 3
	v_readlane_b32 s27, v253, 4
	v_pk_mul_f32 v[6:7], v[6:7], v[8:9]
	v_cvt_pk_bf16_f32 v8, v4, v5
	v_add_u32_e32 v4, s11, v10
	v_ashrrev_i32_e32 v5, 31, v4
	v_cvt_pk_bf16_f32 v9, v6, v7
	v_lshlrev_b64 v[6:7], 11, v[4:5]
	v_lshl_add_u64 v[6:7], v[2:3], 0, v[6:7]
	global_store_dwordx2 v[6:7], v[8:9], off
	ds_read_b128 v[6:9], v0 offset:8448
	v_readlane_b32 s30, v253, 7
	v_readlane_b32 s31, v253, 8
	s_waitcnt lgkmcnt(0)
	v_pk_add_f32 v[6:7], v[6:7], 0 op_sel_hi:[1,0]
	s_nop 0
	v_mul_f32_e32 v5, 0xbfb8aa3b, v6
	v_exp_f32_e32 v5, v5
	v_pk_add_f32 v[8:9], v[8:9], 0 op_sel_hi:[1,0]
	v_add_f32_e32 v5, 1.0, v5
	v_rcp_f32_e32 v10, v5
	v_mul_f32_e32 v5, 0xbfb8aa3b, v7
	v_exp_f32_e32 v5, v5
	s_nop 0
	v_add_f32_e32 v5, 1.0, v5
	v_rcp_f32_e32 v11, v5
	v_mul_f32_e32 v5, 0xbfb8aa3b, v8
	v_exp_f32_e32 v5, v5
	v_pk_mul_f32 v[6:7], v[6:7], v[10:11]
	s_nop 0
	v_cvt_pk_bf16_f32 v6, v6, v7
	v_add_f32_e32 v5, 1.0, v5
	v_rcp_f32_e32 v10, v5
	v_mul_f32_e32 v5, 0xbfb8aa3b, v9
	v_exp_f32_e32 v5, v5
	s_nop 0
	v_add_f32_e32 v5, 1.0, v5
	v_rcp_f32_e32 v11, v5
	s_nop 0
	v_pk_mul_f32 v[8:9], v[8:9], v[10:11]
	s_nop 0
	v_cvt_pk_bf16_f32 v7, v8, v9
	v_add_u32_e32 v8, 16, v4
	v_ashrrev_i32_e32 v9, 31, v8
	v_lshlrev_b64 v[8:9], 11, v[8:9]
	v_lshl_add_u64 v[8:9], v[2:3], 0, v[8:9]
	global_store_dwordx2 v[8:9], v[6:7], off
	ds_read_b128 v[6:9], v0 offset:16896
	s_waitcnt lgkmcnt(0)
; #define TIDX (tid_launder())
; DI unsigned pack2(float a, float b) { hwf2 v = {a, b}; hwbf2 r = __builtin_convertvector(v, hwbf2); return __builtin_bit_cast(unsigned, r); }
; DI float siluf(float x) { return x * __builtin_amdgcn_rcpf(1.f + __expf(-x)); }
; DI void epi_store64(const float* Ct, int cb, const float* rn, int grp, const float* gain, bool silu, const float* bias,
;                     bf16_t* dst, size_t ldd, int dcol0, int m0, int Mmax) {
;   const int tid = TIDX, c = (tid & 15) * 4;
;   float4 gv = make_float4(1.f, 1.f, 1.f, 1.f), bv = make_float4(0.f, 0.f, 0.f, 0.f);
;   if (rn) gv = *(const float4*)(gain + c);
;   if (bias) bv = *(const float4*)(bias + c);
; #pragma unroll
;   for (int q = 0; q < 8; ++q) {
;     const int row = (tid >> 4) + 16 * q;
;     float4 v = *(const float4*)(Ct + row * 132 + cb + c);
;     v.x += bv.x; v.y += bv.y; v.z += bv.z; v.w += bv.w;
;     if (rn) { const float sc = rn[row * 2 + grp]; v.x *= sc * gv.x; v.y *= sc * gv.y; v.z *= sc * gv.z; v.w *= sc * gv.w; }
;     if (silu) { v.x = siluf(v.x); v.y = siluf(v.y); v.z = siluf(v.z); v.w = siluf(v.w); }
;     uint2 o; o.x = pack2(v.x, v.y); o.y = pack2(v.z, v.w);
;     *(uint2*)(dst + (size_t)(m0 + row) * ldd + dcol0 + c) = o;
;   }
	v_pk_add_f32 v[6:7], v[6:7], 0 op_sel_hi:[1,0]
	s_nop 0
	v_mul_f32_e32 v5, 0xbfb8aa3b, v6
	v_exp_f32_e32 v5, v5
	v_pk_add_f32 v[8:9], v[8:9], 0 op_sel_hi:[1,0]
	v_add_f32_e32 v5, 1.0, v5
	v_rcp_f32_e32 v10, v5
	v_mul_f32_e32 v5, 0xbfb8aa3b, v7
	v_exp_f32_e32 v5, v5
	s_nop 0
	v_add_f32_e32 v5, 1.0, v5
	v_rcp_f32_e32 v11, v5
	v_mul_f32_e32 v5, 0xbfb8aa3b, v8
	v_exp_f32_e32 v5, v5
	v_pk_mul_f32 v[6:7], v[6:7], v[10:11]
	s_nop 0
	v_cvt_pk_bf16_f32 v6, v6, v7
	v_add_f32_e32 v5, 1.0, v5
	v_rcp_f32_e32 v10, v5
	v_mul_f32_e32 v5, 0xbfb8aa3b, v9
	v_exp_f32_e32 v5, v5
	s_nop 0
	v_add_f32_e32 v5, 1.0, v5
	v_rcp_f32_e32 v11, v5
	s_nop 0
	v_pk_mul_f32 v[8:9], v[8:9], v[10:11]
	s_nop 0
	v_cvt_pk_bf16_f32 v7, v8, v9
	v_add_u32_e32 v8, 32, v4
	v_ashrrev_i32_e32 v9, 31, v8
	v_lshlrev_b64 v[8:9], 11, v[8:9]
	v_lshl_add_u64 v[8:9], v[2:3], 0, v[8:9]
	global_store_dwordx2 v[8:9], v[6:7], off
	ds_read_b128 v[6:9], v0 offset:25344
	s_waitcnt lgkmcnt(0)
	v_pk_add_f32 v[6:7], v[6:7], 0 op_sel_hi:[1,0]
	s_nop 0
	v_mul_f32_e32 v5, 0xbfb8aa3b, v6
	v_exp_f32_e32 v5, v5
	v_pk_add_f32 v[8:9], v[8:9], 0 op_sel_hi:[1,0]
	v_add_f32_e32 v5, 1.0, v5
	v_rcp_f32_e32 v10, v5
	v_mul_f32_e32 v5, 0xbfb8aa3b, v7
	v_exp_f32_e32 v5, v5
	s_nop 0
	v_add_f32_e32 v5, 1.0, v5
	v_rcp_f32_e32 v11, v5
	v_mul_f32_e32 v5, 0xbfb8aa3b, v8
	v_exp_f32_e32 v5, v5
	v_pk_mul_f32 v[6:7], v[6:7], v[10:11]
	s_nop 0
	v_cvt_pk_bf16_f32 v6, v6, v7
	v_add_f32_e32 v5, 1.0, v5
	v_rcp_f32_e32 v10, v5
	v_mul_f32_e32 v5, 0xbfb8aa3b, v9
	v_exp_f32_e32 v5, v5
	s_nop 0
	v_add_f32_e32 v5, 1.0, v5
	v_rcp_f32_e32 v11, v5
	s_nop 0
	v_pk_mul_f32 v[8:9], v[8:9], v[10:11]
	s_nop 0
	v_cvt_pk_bf16_f32 v7, v8, v9
	v_add_u32_e32 v8, 48, v4
	v_ashrrev_i32_e32 v9, 31, v8
	v_lshlrev_b64 v[8:9], 11, v[8:9]
	v_lshl_add_u64 v[8:9], v[2:3], 0, v[8:9]
	global_store_dwordx2 v[8:9], v[6:7], off
	ds_read_b128 v[6:9], v0 offset:33792
	s_waitcnt lgkmcnt(0)
	v_pk_add_f32 v[6:7], v[6:7], 0 op_sel_hi:[1,0]
	s_nop 0
	v_mul_f32_e32 v5, 0xbfb8aa3b, v6
	v_exp_f32_e32 v5, v5
	v_pk_add_f32 v[8:9], v[8:9], 0 op_sel_hi:[1,0]
	v_add_f32_e32 v5, 1.0, v5
	v_rcp_f32_e32 v10, v5
	v_mul_f32_e32 v5, 0xbfb8aa3b, v7
	v_exp_f32_e32 v5, v5
	s_nop 0
	v_add_f32_e32 v5, 1.0, v5
	v_rcp_f32_e32 v11, v5
	v_mul_f32_e32 v5, 0xbfb8aa3b, v8
	v_exp_f32_e32 v5, v5
	v_pk_mul_f32 v[6:7], v[6:7], v[10:11]
	s_nop 0
	v_cvt_pk_bf16_f32 v6, v6, v7
	v_add_f32_e32 v5, 1.0, v5
	v_rcp_f32_e32 v10, v5
	v_mul_f32_e32 v5, 0xbfb8aa3b, v9
	v_exp_f32_e32 v5, v5
	s_nop 0
	v_add_f32_e32 v5, 1.0, v5
	v_rcp_f32_e32 v11, v5
	s_nop 0
	v_pk_mul_f32 v[8:9], v[8:9], v[10:11]
	s_nop 0
	v_cvt_pk_bf16_f32 v7, v8, v9
	v_add_u32_e32 v8, 64, v4
	v_ashrrev_i32_e32 v9, 31, v8
	v_lshlrev_b64 v[8:9], 11, v[8:9]
	v_lshl_add_u64 v[8:9], v[2:3], 0, v[8:9]
	global_store_dwordx2 v[8:9], v[6:7], off
	ds_read_b128 v[6:9], v0 offset:42240
	s_waitcnt lgkmcnt(0)
	v_pk_add_f32 v[6:7], v[6:7], 0 op_sel_hi:[1,0]
	s_nop 0
	v_mul_f32_e32 v5, 0xbfb8aa3b, v6
	v_exp_f32_e32 v5, v5
	v_pk_add_f32 v[8:9], v[8:9], 0 op_sel_hi:[1,0]
	v_add_f32_e32 v5, 1.0, v5
	v_rcp_f32_e32 v10, v5
	v_mul_f32_e32 v5, 0xbfb8aa3b, v7
	v_exp_f32_e32 v5, v5
	s_nop 0
	v_add_f32_e32 v5, 1.0, v5
	v_rcp_f32_e32 v11, v5
	v_mul_f32_e32 v5, 0xbfb8aa3b, v8
	v_exp_f32_e32 v5, v5
	v_pk_mul_f32 v[6:7], v[6:7], v[10:11]
	s_nop 0
	v_cvt_pk_bf16_f32 v6, v6, v7
	v_add_f32_e32 v5, 1.0, v5
	v_rcp_f32_e32 v10, v5
	v_mul_f32_e32 v5, 0xbfb8aa3b, v9
	v_exp_f32_e32 v5, v5
	s_nop 0
	v_add_f32_e32 v5, 1.0, v5
	v_rcp_f32_e32 v11, v5
	s_nop 0
	v_pk_mul_f32 v[8:9], v[8:9], v[10:11]
	s_nop 0
	v_cvt_pk_bf16_f32 v7, v8, v9
	v_add_u32_e32 v8, 0x50, v4
	v_ashrrev_i32_e32 v9, 31, v8
	v_lshlrev_b64 v[8:9], 11, v[8:9]
	v_lshl_add_u64 v[8:9], v[2:3], 0, v[8:9]
	global_store_dwordx2 v[8:9], v[6:7], off
	ds_read_b128 v[6:9], v0 offset:50688
	s_waitcnt lgkmcnt(0)
	v_pk_add_f32 v[6:7], v[6:7], 0 op_sel_hi:[1,0]
	s_nop 0
	v_mul_f32_e32 v5, 0xbfb8aa3b, v6
	v_exp_f32_e32 v5, v5
	v_pk_add_f32 v[8:9], v[8:9], 0 op_sel_hi:[1,0]
	v_add_f32_e32 v5, 1.0, v5
	v_rcp_f32_e32 v10, v5
	v_mul_f32_e32 v5, 0xbfb8aa3b, v7
	v_exp_f32_e32 v5, v5
	s_nop 0
	v_add_f32_e32 v5, 1.0, v5
	v_rcp_f32_e32 v11, v5
	v_mul_f32_e32 v5, 0xbfb8aa3b, v8
	v_exp_f32_e32 v5, v5
	v_pk_mul_f32 v[6:7], v[6:7], v[10:11]
	s_nop 0
	v_cvt_pk_bf16_f32 v6, v6, v7
	v_add_f32_e32 v5, 1.0, v5
	v_rcp_f32_e32 v10, v5
	v_mul_f32_e32 v5, 0xbfb8aa3b, v9
	v_exp_f32_e32 v5, v5
	s_nop 0
	v_add_f32_e32 v5, 1.0, v5
	v_rcp_f32_e32 v11, v5
	s_nop 0
	v_pk_mul_f32 v[8:9], v[8:9], v[10:11]
	s_nop 0
	v_cvt_pk_bf16_f32 v7, v8, v9
	v_add_u32_e32 v8, 0x60, v4
	v_ashrrev_i32_e32 v9, 31, v8
	v_lshlrev_b64 v[8:9], 11, v[8:9]
	v_lshl_add_u64 v[8:9], v[2:3], 0, v[8:9]
	global_store_dwordx2 v[8:9], v[6:7], off
	ds_read_b128 v[6:9], v0 offset:59136
	v_add_u32_e32 v4, 0x70, v4
	v_ashrrev_i32_e32 v5, 31, v4
	v_lshlrev_b64 v[4:5], 11, v[4:5]
	v_lshl_add_u64 v[2:3], v[2:3], 0, v[4:5]
	s_waitcnt lgkmcnt(0)
	v_pk_add_f32 v[6:7], v[6:7], 0 op_sel_hi:[1,0]
	v_pk_add_f32 v[8:9], v[8:9], 0 op_sel_hi:[1,0]
	v_mul_f32_e32 v0, 0xbfb8aa3b, v6
	v_exp_f32_e32 v0, v0
	s_nop 0
	v_add_f32_e32 v0, 1.0, v0
	v_rcp_f32_e32 v10, v0
	v_mul_f32_e32 v0, 0xbfb8aa3b, v7
	v_exp_f32_e32 v0, v0
	s_nop 0
	v_add_f32_e32 v0, 1.0, v0
	v_rcp_f32_e32 v11, v0
	v_mul_f32_e32 v0, 0xbfb8aa3b, v8
	v_exp_f32_e32 v0, v0
	v_pk_mul_f32 v[6:7], v[6:7], v[10:11]
	s_nop 0
	v_cvt_pk_bf16_f32 v6, v6, v7
	v_add_f32_e32 v0, 1.0, v0
	v_rcp_f32_e32 v10, v0
	v_mul_f32_e32 v0, 0xbfb8aa3b, v9
	v_exp_f32_e32 v0, v0
	s_nop 0
	v_add_f32_e32 v0, 1.0, v0
	v_rcp_f32_e32 v11, v0
	v_mov_b32_e32 v0, v230
	v_pk_mul_f32 v[8:9], v[8:9], v[10:11]
	s_nop 0
	v_cvt_pk_bf16_f32 v7, v8, v9
	global_store_dwordx2 v[2:3], v[6:7], off
	s_nop 0
	v_lshlrev_b32_e32 v2, 2, v0
	v_and_b32_e32 v4, 60, v2
	v_ashrrev_i32_e32 v10, 4, v0
	v_lshlrev_b32_e32 v0, 1, v4
	v_lshl_add_u64 v[2:3], s[0:1], 0, v[0:1]
	v_mul_lo_u32 v0, v10, s79
	v_lshl_add_u32 v0, v4, 2, v0
	ds_read_b128 v[4:7], v0 offset:256
	s_movk_i32 s0, 0xe780
	s_mov_b32 s1, -1
	v_lshl_add_u64 v[2:3], v[2:3], 0, s[0:1]
	s_mov_b64 s[0:1], 0
	s_waitcnt lgkmcnt(0)
; DI unsigned pack2(float a, float b) { hwf2 v = {a, b}; hwbf2 r = __builtin_convertvector(v, hwbf2); return __builtin_bit_cast(unsigned, r); }
; DI float siluf(float x) { return x * __builtin_amdgcn_rcpf(1.f + __expf(-x)); }
; DI void epi_store64(const float* Ct, int cb, const float* rn, int grp, const float* gain, bool silu, const float* bias,
;                     bf16_t* dst, size_t ldd, int dcol0, int m0, int Mmax) {
;     ...
;   for (int q = 0; q < 8; ++q) {
;     const int row = (tid >> 4) + 16 * q;
;     float4 v = *(const float4*)(Ct + row * 132 + cb + c);
;     v.x += bv.x; v.y += bv.y; v.z += bv.z; v.w += bv.w;
;     if (rn) { const float sc = rn[row * 2 + grp]; v.x *= sc * gv.x; v.y *= sc * gv.y; v.z *= sc * gv.z; v.w *= sc * gv.w; }
;     if (silu) { v.x = siluf(v.x); v.y = siluf(v.y); v.z = siluf(v.z); v.w = siluf(v.w); }
;     uint2 o; o.x = pack2(v.x, v.y); o.y = pack2(v.z, v.w);
;     *(uint2*)(dst + (size_t)(m0 + row) * ldd + dcol0 + c) = o;
;   }
	v_pk_add_f32 v[4:5], v[4:5], 0 op_sel_hi:[1,0]
	v_pk_add_f32 v[6:7], v[6:7], 0 op_sel_hi:[1,0]
	v_mul_f32_e32 v8, 0xbfb8aa3b, v4
	v_mul_f32_e32 v9, 0xbfb8aa3b, v5
	v_exp_f32_e32 v8, v8
	v_exp_f32_e32 v9, v9
	v_add_f32_e32 v8, 1.0, v8
	v_add_f32_e32 v9, 1.0, v9
	v_rcp_f32_e32 v8, v8
	v_rcp_f32_e32 v9, v9
	s_nop 0
	v_pk_mul_f32 v[4:5], v[4:5], v[8:9]
	v_mul_f32_e32 v8, 0xbfb8aa3b, v6
	v_mul_f32_e32 v9, 0xbfb8aa3b, v7
	v_exp_f32_e32 v8, v8
	v_exp_f32_e32 v9, v9
	v_add_f32_e32 v8, 1.0, v8
	v_add_f32_e32 v9, 1.0, v9
	v_rcp_f32_e32 v8, v8
	v_rcp_f32_e32 v9, v9
	s_nop 0
	v_pk_mul_f32 v[6:7], v[6:7], v[8:9]
	v_cvt_pk_bf16_f32 v8, v4, v5
	v_add_u32_e32 v4, s11, v10
	v_ashrrev_i32_e32 v5, 31, v4
	v_cvt_pk_bf16_f32 v9, v6, v7
	v_lshlrev_b64 v[6:7], 11, v[4:5]
	v_lshl_add_u64 v[6:7], v[2:3], 0, v[6:7]
	global_store_dwordx2 v[6:7], v[8:9], off
	ds_read_b128 v[6:9], v0 offset:8704
	s_waitcnt lgkmcnt(0)
	v_pk_add_f32 v[6:7], v[6:7], 0 op_sel_hi:[1,0]
	s_nop 0
	v_mul_f32_e32 v5, 0xbfb8aa3b, v6
	v_exp_f32_e32 v5, v5
	v_pk_add_f32 v[8:9], v[8:9], 0 op_sel_hi:[1,0]
	v_add_f32_e32 v5, 1.0, v5
	v_rcp_f32_e32 v10, v5
	v_mul_f32_e32 v5, 0xbfb8aa3b, v7
	v_exp_f32_e32 v5, v5
	s_nop 0
	v_add_f32_e32 v5, 1.0, v5
	v_rcp_f32_e32 v11, v5
	v_mul_f32_e32 v5, 0xbfb8aa3b, v8
	v_exp_f32_e32 v5, v5
	v_pk_mul_f32 v[6:7], v[6:7], v[10:11]
	s_nop 0
	v_cvt_pk_bf16_f32 v6, v6, v7
	v_add_f32_e32 v5, 1.0, v5
	v_rcp_f32_e32 v10, v5
	v_mul_f32_e32 v5, 0xbfb8aa3b, v9
	v_exp_f32_e32 v5, v5
	s_nop 0
	v_add_f32_e32 v5, 1.0, v5
	v_rcp_f32_e32 v11, v5
	s_nop 0
	v_pk_mul_f32 v[8:9], v[8:9], v[10:11]
	s_nop 0
	v_cvt_pk_bf16_f32 v7, v8, v9
	v_add_u32_e32 v8, 16, v4
	v_ashrrev_i32_e32 v9, 31, v8
	v_lshlrev_b64 v[8:9], 11, v[8:9]
	v_lshl_add_u64 v[8:9], v[2:3], 0, v[8:9]
	global_store_dwordx2 v[8:9], v[6:7], off
	ds_read_b128 v[6:9], v0 offset:17152
	s_waitcnt lgkmcnt(0)
	v_pk_add_f32 v[6:7], v[6:7], 0 op_sel_hi:[1,0]
	s_nop 0
	v_mul_f32_e32 v5, 0xbfb8aa3b, v6
	v_exp_f32_e32 v5, v5
	v_pk_add_f32 v[8:9], v[8:9], 0 op_sel_hi:[1,0]
	v_add_f32_e32 v5, 1.0, v5
	v_rcp_f32_e32 v10, v5
	v_mul_f32_e32 v5, 0xbfb8aa3b, v7
	v_exp_f32_e32 v5, v5
	s_nop 0
	v_add_f32_e32 v5, 1.0, v5
	v_rcp_f32_e32 v11, v5
	v_mul_f32_e32 v5, 0xbfb8aa3b, v8
	v_exp_f32_e32 v5, v5
	v_pk_mul_f32 v[6:7], v[6:7], v[10:11]
	s_nop 0
	v_cvt_pk_bf16_f32 v6, v6, v7
	v_add_f32_e32 v5, 1.0, v5
	v_rcp_f32_e32 v10, v5
	v_mul_f32_e32 v5, 0xbfb8aa3b, v9
	v_exp_f32_e32 v5, v5
	s_nop 0
	v_add_f32_e32 v5, 1.0, v5
	v_rcp_f32_e32 v11, v5
	s_nop 0
	v_pk_mul_f32 v[8:9], v[8:9], v[10:11]
	s_nop 0
	v_cvt_pk_bf16_f32 v7, v8, v9
	v_add_u32_e32 v8, 32, v4
	v_ashrrev_i32_e32 v9, 31, v8
	v_lshlrev_b64 v[8:9], 11, v[8:9]
	v_lshl_add_u64 v[8:9], v[2:3], 0, v[8:9]
	global_store_dwordx2 v[8:9], v[6:7], off
	ds_read_b128 v[6:9], v0 offset:25600
	s_waitcnt lgkmcnt(0)
	v_pk_add_f32 v[6:7], v[6:7], 0 op_sel_hi:[1,0]
	s_nop 0
	v_mul_f32_e32 v5, 0xbfb8aa3b, v6
	v_exp_f32_e32 v5, v5
	v_pk_add_f32 v[8:9], v[8:9], 0 op_sel_hi:[1,0]
	v_add_f32_e32 v5, 1.0, v5
	v_rcp_f32_e32 v10, v5
	v_mul_f32_e32 v5, 0xbfb8aa3b, v7
	v_exp_f32_e32 v5, v5
	s_nop 0
	v_add_f32_e32 v5, 1.0, v5
	v_rcp_f32_e32 v11, v5
	v_mul_f32_e32 v5, 0xbfb8aa3b, v8
	v_exp_f32_e32 v5, v5
	v_pk_mul_f32 v[6:7], v[6:7], v[10:11]
	s_nop 0
	v_cvt_pk_bf16_f32 v6, v6, v7
	v_add_f32_e32 v5, 1.0, v5
	v_rcp_f32_e32 v10, v5
	v_mul_f32_e32 v5, 0xbfb8aa3b, v9
	v_exp_f32_e32 v5, v5
	s_nop 0
	v_add_f32_e32 v5, 1.0, v5
	v_rcp_f32_e32 v11, v5
	s_nop 0
	v_pk_mul_f32 v[8:9], v[8:9], v[10:11]
	s_nop 0
	v_cvt_pk_bf16_f32 v7, v8, v9
	v_add_u32_e32 v8, 48, v4
	v_ashrrev_i32_e32 v9, 31, v8
	v_lshlrev_b64 v[8:9], 11, v[8:9]
	v_lshl_add_u64 v[8:9], v[2:3], 0, v[8:9]
	global_store_dwordx2 v[8:9], v[6:7], off
	ds_read_b128 v[6:9], v0 offset:34048
	s_waitcnt lgkmcnt(0)
; DI unsigned pack2(float a, float b) { hwf2 v = {a, b}; hwbf2 r = __builtin_convertvector(v, hwbf2); return __builtin_bit_cast(unsigned, r); }
; DI float siluf(float x) { return x * __builtin_amdgcn_rcpf(1.f + __expf(-x)); }
; DI void epi_store64(const float* Ct, int cb, const float* rn, int grp, const float* gain, bool silu, const float* bias,
;                     bf16_t* dst, size_t ldd, int dcol0, int m0, int Mmax) {
;     ...
;   for (int q = 0; q < 8; ++q) {
;     const int row = (tid >> 4) + 16 * q;
;     float4 v = *(const float4*)(Ct + row * 132 + cb + c);
;     v.x += bv.x; v.y += bv.y; v.z += bv.z; v.w += bv.w;
;     if (rn) { const float sc = rn[row * 2 + grp]; v.x *= sc * gv.x; v.y *= sc * gv.y; v.z *= sc * gv.z; v.w *= sc * gv.w; }
;     if (silu) { v.x = siluf(v.x); v.y = siluf(v.y); v.z = siluf(v.z); v.w = siluf(v.w); }
;     uint2 o; o.x = pack2(v.x, v.y); o.y = pack2(v.z, v.w);
;     *(uint2*)(dst + (size_t)(m0 + row) * ldd + dcol0 + c) = o;
;   }
	v_pk_add_f32 v[6:7], v[6:7], 0 op_sel_hi:[1,0]
	s_nop 0
	v_mul_f32_e32 v5, 0xbfb8aa3b, v6
	v_exp_f32_e32 v5, v5
	v_pk_add_f32 v[8:9], v[8:9], 0 op_sel_hi:[1,0]
	v_add_f32_e32 v5, 1.0, v5
	v_rcp_f32_e32 v10, v5
	v_mul_f32_e32 v5, 0xbfb8aa3b, v7
	v_exp_f32_e32 v5, v5
	s_nop 0
	v_add_f32_e32 v5, 1.0, v5
	v_rcp_f32_e32 v11, v5
	v_mul_f32_e32 v5, 0xbfb8aa3b, v8
	v_exp_f32_e32 v5, v5
	v_pk_mul_f32 v[6:7], v[6:7], v[10:11]
	s_nop 0
	v_cvt_pk_bf16_f32 v6, v6, v7
	v_add_f32_e32 v5, 1.0, v5
	v_rcp_f32_e32 v10, v5
	v_mul_f32_e32 v5, 0xbfb8aa3b, v9
	v_exp_f32_e32 v5, v5
	s_nop 0
	v_add_f32_e32 v5, 1.0, v5
	v_rcp_f32_e32 v11, v5
	s_nop 0
	v_pk_mul_f32 v[8:9], v[8:9], v[10:11]
	s_nop 0
	v_cvt_pk_bf16_f32 v7, v8, v9
	v_add_u32_e32 v8, 64, v4
	v_ashrrev_i32_e32 v9, 31, v8
	v_lshlrev_b64 v[8:9], 11, v[8:9]
	v_lshl_add_u64 v[8:9], v[2:3], 0, v[8:9]
	global_store_dwordx2 v[8:9], v[6:7], off
	ds_read_b128 v[6:9], v0 offset:42496
	s_waitcnt lgkmcnt(0)
	v_pk_add_f32 v[6:7], v[6:7], 0 op_sel_hi:[1,0]
	s_nop 0
	v_mul_f32_e32 v5, 0xbfb8aa3b, v6
	v_exp_f32_e32 v5, v5
	v_pk_add_f32 v[8:9], v[8:9], 0 op_sel_hi:[1,0]
	v_add_f32_e32 v5, 1.0, v5
	v_rcp_f32_e32 v10, v5
	v_mul_f32_e32 v5, 0xbfb8aa3b, v7
	v_exp_f32_e32 v5, v5
	s_nop 0
	v_add_f32_e32 v5, 1.0, v5
	v_rcp_f32_e32 v11, v5
	v_mul_f32_e32 v5, 0xbfb8aa3b, v8
	v_exp_f32_e32 v5, v5
	v_pk_mul_f32 v[6:7], v[6:7], v[10:11]
	s_nop 0
	v_cvt_pk_bf16_f32 v6, v6, v7
	v_add_f32_e32 v5, 1.0, v5
	v_rcp_f32_e32 v10, v5
	v_mul_f32_e32 v5, 0xbfb8aa3b, v9
	v_exp_f32_e32 v5, v5
	s_nop 0
	v_add_f32_e32 v5, 1.0, v5
	v_rcp_f32_e32 v11, v5
	s_nop 0
	v_pk_mul_f32 v[8:9], v[8:9], v[10:11]
	s_nop 0
	v_cvt_pk_bf16_f32 v7, v8, v9
	v_add_u32_e32 v8, 0x50, v4
	v_ashrrev_i32_e32 v9, 31, v8
	v_lshlrev_b64 v[8:9], 11, v[8:9]
	v_lshl_add_u64 v[8:9], v[2:3], 0, v[8:9]
	global_store_dwordx2 v[8:9], v[6:7], off
	ds_read_b128 v[6:9], v0 offset:50944
	s_waitcnt lgkmcnt(0)
	v_pk_add_f32 v[6:7], v[6:7], 0 op_sel_hi:[1,0]
	s_nop 0
	v_mul_f32_e32 v5, 0xbfb8aa3b, v6
	v_exp_f32_e32 v5, v5
	v_pk_add_f32 v[8:9], v[8:9], 0 op_sel_hi:[1,0]
	v_add_f32_e32 v5, 1.0, v5
	v_rcp_f32_e32 v10, v5
	v_mul_f32_e32 v5, 0xbfb8aa3b, v7
	v_exp_f32_e32 v5, v5
	s_nop 0
	v_add_f32_e32 v5, 1.0, v5
	v_rcp_f32_e32 v11, v5
	v_mul_f32_e32 v5, 0xbfb8aa3b, v8
	v_exp_f32_e32 v5, v5
	v_pk_mul_f32 v[6:7], v[6:7], v[10:11]
	s_nop 0
	v_cvt_pk_bf16_f32 v6, v6, v7
	v_add_f32_e32 v5, 1.0, v5
	v_rcp_f32_e32 v10, v5
	v_mul_f32_e32 v5, 0xbfb8aa3b, v9
	v_exp_f32_e32 v5, v5
	s_nop 0
	v_add_f32_e32 v5, 1.0, v5
	v_rcp_f32_e32 v11, v5
	s_nop 0
	v_pk_mul_f32 v[8:9], v[8:9], v[10:11]
	s_nop 0
	v_cvt_pk_bf16_f32 v7, v8, v9
	v_add_u32_e32 v8, 0x60, v4
	v_ashrrev_i32_e32 v9, 31, v8
	v_lshlrev_b64 v[8:9], 11, v[8:9]
	v_lshl_add_u64 v[8:9], v[2:3], 0, v[8:9]
	global_store_dwordx2 v[8:9], v[6:7], off
	ds_read_b128 v[6:9], v0 offset:59392
	v_add_u32_e32 v4, 0x70, v4
	v_ashrrev_i32_e32 v5, 31, v4
	v_lshlrev_b64 v[4:5], 11, v[4:5]
	v_lshl_add_u64 v[2:3], v[2:3], 0, v[4:5]
	s_waitcnt lgkmcnt(0)
	v_pk_add_f32 v[6:7], v[6:7], 0 op_sel_hi:[1,0]
	v_pk_add_f32 v[8:9], v[8:9], 0 op_sel_hi:[1,0]
	v_mul_f32_e32 v0, 0xbfb8aa3b, v6
	v_exp_f32_e32 v0, v0
	s_nop 0
	v_add_f32_e32 v0, 1.0, v0
	v_rcp_f32_e32 v10, v0
	v_mul_f32_e32 v0, 0xbfb8aa3b, v7
	v_exp_f32_e32 v0, v0
	s_nop 0
	v_add_f32_e32 v0, 1.0, v0
	v_rcp_f32_e32 v11, v0
	v_mul_f32_e32 v0, 0xbfb8aa3b, v8
	v_exp_f32_e32 v0, v0
	v_pk_mul_f32 v[6:7], v[6:7], v[10:11]
	s_nop 0
	v_cvt_pk_bf16_f32 v6, v6, v7
	v_add_f32_e32 v0, 1.0, v0
	v_rcp_f32_e32 v10, v0
	v_mul_f32_e32 v0, 0xbfb8aa3b, v9
	v_exp_f32_e32 v0, v0
	s_nop 0
	v_add_f32_e32 v0, 1.0, v0
	v_rcp_f32_e32 v11, v0
	s_nop 0
	v_pk_mul_f32 v[8:9], v[8:9], v[10:11]
	s_nop 0
	v_cvt_pk_bf16_f32 v7, v8, v9
	global_store_dwordx2 v[2:3], v[6:7], off

; #define G_STORE(ST, S, unused) do { char* d_ = smem + (ST) * STAGE; \
;     *(uint4*)(d_ + alo[0]) = S##a0; *(uint4*)(d_ + alo[1]) = S##a1; *(uint4*)(d_ + alo[2]) = S##a2; *(uint4*)(d_ + alo[3]) = S##a3; \
;     *(uint4*)(d_ + blo[0]) = S##b0; *(uint4*)(d_ + blo[1]) = S##b1; \
;     if (NBCH == 4) { *(uint4*)(d_ + blo[NBCH - 2]) = S##b2; *(uint4*)(d_ + blo[NBCH - 1]) = S##b3; } } while (0)
; template <int NJ, class RowA>
; DI void gemm_main(f32x16 (&acc)[2][NJ], const bf16_t* __restrict__ A, RowA rowA, size_t kstrideA, int m0, int Mmax,
;                   const bf16_t* __restrict__ Bt, size_t ldb, int n0, int nk, char* smem) {
;     ...
;   __syncthreads();
;   G_LOAD(x0, 0, 0);
;   G_LOAD(x1, 0, 1);
;   G_STORE(0, x0, 0);
;   __syncthreads();
; #pragma unroll 1
;   for (int kt = 0; kt < nk; kt += 2) {
;     G_LOAD(x0, 0, (kt + 2 < nk ? kt + 2 : nk - 1));
;     G_COMPUTE(0);
;     G_STORE(1, x1, 0);
;     __syncthreads();
;     G_LOAD(x1, 0, (kt + 3 < nk ? kt + 3 : nk - 1));
;     G_COMPUTE(1);
;     G_STORE(0, x0, 0);
;     __syncthreads();
.Lpeel_tail_2149:
	ds_read_b128 v[166:169], v0
	ds_read_b128 v[170:173], v139 offset:18432
	ds_read_b128 v[174:177], v139 offset:23040
	ds_read_b128 v[178:181], v0 offset:4608
	s_add_i32 s1, s0, 4
	s_min_u32 s1, s1, 15
	s_lshl_b32 s14, s1, 7
	v_lshl_add_u64 v[98:99], v[122:123], 0, s[14:15]
	v_lshl_add_u64 v[102:103], v[124:125], 0, s[14:15]
	v_lshl_add_u64 v[106:107], v[126:127], 0, s[14:15]
	v_lshl_add_u64 v[110:111], v[128:129], 0, s[14:15]
	v_lshl_add_u64 v[114:115], v[130:131], 0, s[14:15]
	v_lshl_add_u64 v[118:119], v[132:133], 0, s[14:15]
	s_add_i32 s0, s0, 2
	v_lshl_add_u64 v[158:159], v[134:135], 0, s[14:15]
	v_lshl_add_u64 v[160:161], v[136:137], 0, s[14:15]
	ds_read_b128 v[182:185], v0 offset:32
	ds_read_b128 v[186:189], v139 offset:18464
	ds_read_b128 v[190:193], v139 offset:23072
	ds_read_b128 v[194:197], v0 offset:4640
	s_waitcnt lgkmcnt(4)
	v_mfma_f32_32x32x16_bf16 v[50:65], v[166:169], v[170:173], v[50:65]
	v_mfma_f32_32x32x16_bf16 v[34:49], v[166:169], v[174:177], v[34:49]
	v_mfma_f32_32x32x16_bf16 v[18:33], v[178:181], v[170:173], v[18:33]
	v_mfma_f32_32x32x16_bf16 v[2:17], v[178:181], v[174:177], v[2:17]
	ds_read_b128 v[166:169], v0 offset:64
	ds_read_b128 v[170:173], v139 offset:18496
	ds_read_b128 v[174:177], v139 offset:23104
	ds_read_b128 v[178:181], v0 offset:4672
	s_waitcnt lgkmcnt(4)
	v_mfma_f32_32x32x16_bf16 v[50:65], v[182:185], v[186:189], v[50:65]
	v_mfma_f32_32x32x16_bf16 v[34:49], v[182:185], v[190:193], v[34:49]
	v_mfma_f32_32x32x16_bf16 v[18:33], v[194:197], v[186:189], v[18:33]
	v_mfma_f32_32x32x16_bf16 v[2:17], v[194:197], v[190:193], v[2:17]
	ds_read_b128 v[182:185], v0 offset:96
	ds_read_b128 v[186:189], v139 offset:18528
	ds_read_b128 v[190:193], v139 offset:23136
	ds_read_b128 v[194:197], v0 offset:4704
	s_waitcnt lgkmcnt(4)
	v_mfma_f32_32x32x16_bf16 v[50:65], v[166:169], v[170:173], v[50:65]
	s_waitcnt vmcnt(0)
	ds_write_b128 v138, v[74:77] offset:36864
	v_mfma_f32_32x32x16_bf16 v[34:49], v[166:169], v[174:177], v[34:49]
	ds_write_b128 v140, v[78:81] offset:36864
	v_mfma_f32_32x32x16_bf16 v[18:33], v[178:181], v[170:173], v[18:33]
	ds_write_b128 v142, v[82:85] offset:36864
	v_mfma_f32_32x32x16_bf16 v[2:17], v[178:181], v[174:177], v[2:17]
	ds_write_b128 v144, v[86:89] offset:36864
	s_waitcnt lgkmcnt(4)
	v_mfma_f32_32x32x16_bf16 v[50:65], v[182:185], v[186:189], v[50:65]
	ds_write_b128 v138, v[90:93] offset:55296
	v_mfma_f32_32x32x16_bf16 v[34:49], v[182:185], v[190:193], v[34:49]
	ds_write_b128 v140, v[94:97] offset:55296
	v_mfma_f32_32x32x16_bf16 v[18:33], v[194:197], v[186:189], v[18:33]
	ds_write_b128 v142, v[66:69] offset:55296
	v_mfma_f32_32x32x16_bf16 v[2:17], v[194:197], v[190:193], v[2:17]
	ds_write_b128 v144, v[70:73] offset:55296
	s_min_u32 s1, s0, 12
	s_lshl_b32 s14, s1, 7
	v_lshl_add_u64 v[66:67], v[122:123], 0, s[14:15]
	v_lshl_add_u64 v[68:69], v[124:125], 0, s[14:15]
	v_lshl_add_u64 v[70:71], v[126:127], 0, s[14:15]
	v_lshl_add_u64 v[72:73], v[128:129], 0, s[14:15]
	v_lshl_add_u64 v[90:91], v[130:131], 0, s[14:15]
	v_lshl_add_u64 v[94:95], v[132:133], 0, s[14:15]
	s_waitcnt lgkmcnt(0)
	s_barrier
	ds_read_b128 v[166:169], v0 offset:36864
	ds_read_b128 v[170:173], v139 offset:55296
	ds_read_b128 v[174:177], v139 offset:59904
	ds_read_b128 v[178:181], v0 offset:41472
	v_lshl_add_u64 v[154:155], v[134:135], 0, s[14:15]
	v_lshl_add_u64 v[156:157], v[136:137], 0, s[14:15]
	ds_read_b128 v[182:185], v0 offset:36896
	ds_read_b128 v[186:189], v139 offset:55328
	ds_read_b128 v[190:193], v139 offset:59936
	ds_read_b128 v[194:197], v0 offset:41504
	s_waitcnt lgkmcnt(4)
	v_mfma_f32_32x32x16_bf16 v[50:65], v[166:169], v[170:173], v[50:65]
	v_mfma_f32_32x32x16_bf16 v[34:49], v[166:169], v[174:177], v[34:49]
	v_mfma_f32_32x32x16_bf16 v[18:33], v[178:181], v[170:173], v[18:33]
	v_mfma_f32_32x32x16_bf16 v[2:17], v[178:181], v[174:177], v[2:17]
	ds_read_b128 v[166:169], v0 offset:36928
	ds_read_b128 v[170:173], v139 offset:55360
	ds_read_b128 v[174:177], v139 offset:59968
	ds_read_b128 v[178:181], v0 offset:41536
	s_waitcnt lgkmcnt(4)
	v_mfma_f32_32x32x16_bf16 v[50:65], v[182:185], v[186:189], v[50:65]
	v_mfma_f32_32x32x16_bf16 v[34:49], v[182:185], v[190:193], v[34:49]
	v_mfma_f32_32x32x16_bf16 v[18:33], v[194:197], v[186:189], v[18:33]
	v_mfma_f32_32x32x16_bf16 v[2:17], v[194:197], v[190:193], v[2:17]
	ds_read_b128 v[182:185], v0 offset:36960
	ds_read_b128 v[186:189], v139 offset:55392
	ds_read_b128 v[190:193], v139 offset:60000
	ds_read_b128 v[194:197], v0 offset:41568
	s_waitcnt lgkmcnt(4)
	v_mfma_f32_32x32x16_bf16 v[50:65], v[166:169], v[170:173], v[50:65]
	v_mfma_f32_32x32x16_bf16 v[34:49], v[166:169], v[174:177], v[34:49]
	v_mfma_f32_32x32x16_bf16 v[18:33], v[178:181], v[170:173], v[18:33]
	v_mfma_f32_32x32x16_bf16 v[2:17], v[178:181], v[174:177], v[2:17]
	s_waitcnt lgkmcnt(0)
	v_mfma_f32_32x32x16_bf16 v[50:65], v[182:185], v[186:189], v[50:65]
	v_mfma_f32_32x32x16_bf16 v[34:49], v[182:185], v[190:193], v[34:49]
	v_mfma_f32_32x32x16_bf16 v[18:33], v[194:197], v[186:189], v[18:33]
	v_mfma_f32_32x32x16_bf16 v[2:17], v[194:197], v[190:193], v[2:17]
	s_cmp_lt_u32 s0, 14
	s_waitcnt lgkmcnt(0)
	s_barrier
; template <int NJ>
; DI void acc_to_ct(const f32x16 (&acc)[2][NJ], float* Ct) {
;   const int lane = TIDX & 63, wid = TIDX >> 6, wm = wid >> 1, wn = wid & 1;
;   const int r = lane & 31, hh = lane >> 5;
; #pragma unroll
;   for (int i = 0; i < 2; ++i)
; #pragma unroll
;     for (int j = 0; j < NJ; ++j)
; #pragma unroll
;       for (int e = 0; e < 16; ++e) Ct[(wm * 64 + i * 32 + crow(e, hh)) * 132 + wn * 32 * NJ + j * 32 + r] = acc[i][j][e];
;   __syncthreads();
; DI void inproj_tile(const Params& p, int l, int mt, int tn, char* smem) {
;     ...
;   if (tn <= 3) {
;     epi_rownorm(Ct, rn, 64);
;     const float* g = tn < 2 ? p.a_q_norm + l * 64 : p.c_q_norm + l * 64;
;     epi_store64(Ct, 0, rn, 0, g, false, nullptr, p.projA, LDA_A, tn * 128, m0, T_TOK);
;     epi_store64(Ct, 64, rn, 1, g, false, nullptr, p.projA, LDA_A, tn * 128 + 64, m0, T_TOK);
;   } else if (tn == 4) {
;     epi_rownorm(Ct, rn, 128);
;     const float* g = p.a_kv_norm + l * 128;
;     epi_store64(Ct, 0, rn, 0, g, false, nullptr, p.projA, LDA_A, 512, m0, T_TOK);
;     epi_store64(Ct, 64, rn, 1, g + 64, false, nullptr, p.projA, LDA_A, 576, m0, T_TOK);
;   } else if (tn <= 8) {
;     epi_store64(Ct, 0, nullptr, 0, nullptr, false, nullptr, p.projA, LDA_A, tn * 128, m0, T_TOK);
;     epi_store64(Ct, 64, nullptr, 0, nullptr, false, nullptr, p.projA, LDA_A, tn * 128 + 64, m0, T_TOK);
;   } else if (tn == 9) {
;     epi_storeKF(Ct, 0, nullptr, 0, nullptr, p.kidxF + ((size_t)b * 64 + s0 / 32) * 2048);
;     epi_store64(Ct, 64, nullptr, 0, nullptr, false, nullptr, p.projA, LDA_A, tn * 128 + 64, m0, T_TOK);
;   } else if (tn == 10) {
;     epi_rownorm(Ct, rn, 64);
;     epi_store64(Ct, 0, nullptr, 0, nullptr, false, nullptr, p.projA, LDA_A, 1280, m0, T_TOK);
;     epi_storeKF(Ct, 64, rn, 1, p.c_k_norm + (l * 3 + 1) * 64, p.kselF + ((size_t)b * 64 + s0 / 32) * 2048);
;   } else if (tn == 11) {
;     epi_rownorm(Ct, rn, 64);
;     epi_storeKF(Ct, 0, rn, 0, p.c_k_norm + (l * 3 + 2) * 64, p.kwinF + ((size_t)b * 64 + s0 / 32) * 2048);
;     epi_storeVF(Ct, 64, p.vselT + ((size_t)b * 64 + s0 / 32) * 2048);
;   } else if (tn == 12) {
;     epi_storeVF(Ct, 0, p.vwinT + ((size_t)b * 64 + s0 / 32) * 2048);
;     for (int idx = TIDX; idx < 128 * 32; idx += 256) {
;       const int row = idx >> 5, c = idx & 31;
;       p.small[(size_t)(m0 + row) * 32 + c] = Ct[row * 132 + 64 + c];
;     }
;   } else if (tn <= 24) {
	v_mov_b32_e32 v0, v230
	s_waitcnt vmcnt(1)
	v_mov_b32_e32 v66, v230
	v_and_b32_e32 v67, 31, v0
	v_lshrrev_b32_e32 v0, 3, v0
	v_and_b32_e32 v0, 4, v0
	v_lshrrev_b32_e32 v68, 1, v66
	v_and_or_b32 v0, v68, s47, v0
	v_and_or_b32 v66, v66, 64, v67
	v_mul_lo_u32 v0, v0, s79
	v_lshl_add_u32 v0, v66, 2, v0
	ds_write2_b32 v0, v50, v34 offset1:32
	ds_write2_b32 v0, v51, v35 offset0:132 offset1:164
	v_add_u32_e32 v34, 0x400, v0
	ds_write2_b32 v34, v52, v36 offset0:8 offset1:40
	ds_write2_b32 v34, v53, v37 offset0:140 offset1:172
	v_add_u32_e32 v34, 0x1000, v0
	ds_write2_b32 v34, v54, v38 offset0:32 offset1:64
	ds_write2_b32 v34, v55, v39 offset0:164 offset1:196
	v_add_u32_e32 v34, 0x1400, v0
	ds_write2_b32 v34, v56, v40 offset0:40 offset1:72
	ds_write2_b32 v34, v57, v41 offset0:172 offset1:204
	v_add_u32_e32 v34, 0x2000, v0
	ds_write2_b32 v34, v58, v42 offset0:64 offset1:96
	ds_write2_b32 v34, v59, v43 offset0:196 offset1:228
	v_add_u32_e32 v34, 0x2400, v0
	ds_write2_b32 v34, v60, v44 offset0:72 offset1:104
	ds_write2_b32 v34, v61, v45 offset0:204 offset1:236
	v_add_u32_e32 v34, 0x3000, v0
	ds_write2_b32 v34, v62, v46 offset0:96 offset1:128
	v_add_u32_e32 v34, 0x3200, v0
	ds_write2_b32 v34, v63, v47 offset0:100 offset1:132
	v_add_u32_e32 v34, 0x3400, v0
	ds_write2_b32 v34, v64, v48 offset0:104 offset1:136
	v_add_u32_e32 v34, 0x3600, v0
	ds_write2_b32 v34, v65, v49 offset0:108 offset1:140
	v_add_u32_e32 v34, 0x4000, v0
	ds_write2_b32 v34, v18, v2 offset0:128 offset1:160
	v_add_u32_e32 v2, 0x4400, v0
	ds_write2_b32 v2, v19, v3 offset0:4 offset1:36
	ds_write2_b32 v2, v20, v4 offset0:136 offset1:168
	v_add_u32_e32 v2, 0x4800, v0
	ds_write2_b32 v2, v21, v5 offset0:12 offset1:44
	v_add_u32_e32 v2, 0x5000, v0
	ds_write2_b32 v2, v22, v6 offset0:160 offset1:192
	v_add_u32_e32 v2, 0x5400, v0
	ds_write2_b32 v2, v23, v7 offset0:36 offset1:68
	ds_write2_b32 v2, v24, v8 offset0:168 offset1:200
	v_add_u32_e32 v2, 0x5800, v0
	ds_write2_b32 v2, v25, v9 offset0:44 offset1:76
	v_add_u32_e32 v2, 0x6000, v0
	ds_write2_b32 v2, v26, v10 offset0:192 offset1:224
	v_add_u32_e32 v2, 0x6400, v0
	ds_write2_b32 v2, v27, v11 offset0:68 offset1:100
	ds_write2_b32 v2, v28, v12 offset0:200 offset1:232
	v_add_u32_e32 v2, 0x6800, v0
	ds_write2_b32 v2, v29, v13 offset0:76 offset1:108
	v_add_u32_e32 v2, 0x7200, v0
	ds_write2_b32 v2, v30, v14 offset0:96 offset1:128
	v_add_u32_e32 v2, 0x7400, v0
	ds_write2_b32 v2, v31, v15 offset0:100 offset1:132
	v_add_u32_e32 v2, 0x7600, v0
	v_add_u32_e32 v0, 0x7800, v0
	s_cmp_gt_u32 s35, 3
	s_mov_b64 s[0:1], -1
	ds_write2_b32 v2, v32, v16 offset0:104 offset1:136
	ds_write2_b32 v0, v33, v17 offset0:108 offset1:140
	s_waitcnt lgkmcnt(0)
	s_barrier
	s_cbranch_scc0 .LBB0_2277
	s_cmp_lg_u32 s35, 4
	s_cbranch_scc0 .LBB0_2236
	s_cmp_gt_u32 s35, 8
	s_cbranch_scc0 .LBB0_2233
	s_ashr_i32 s0, s2, 6
	s_add_i32 s2, s0, s3
	s_ashr_i32 s0, s13, 31
	s_lshr_b32 s0, s0, 21
	s_add_i32 s0, s13, s0
	s_and_b32 s0, s0, 0xfffff800
	s_sub_i32 s14, s13, s0
	s_mov_b64 s[0:1], -1
	s_mov_b64 s[6:7], 0
	s_cmp_lt_i32 s68, -1
	s_mov_b64 s[4:5], 0
	s_cbranch_scc1 .LBB0_2199
	s_cmp_gt_i32 s68, -1
	s_cbranch_scc0 .LBB0_2169
	s_cmp_eq_u32 s68, 0
	s_mov_b64 s[4:5], -1
	s_cbranch_scc0 .LBB0_2168
	v_mov_b32_e32 v2, v230
	s_movk_i32 s0, 0x400
	s_nop 0
	v_cmp_gt_i32_e32 vcc, s0, v2
	s_and_saveexec_b64 s[0:1], vcc
	s_movk_i32 s36, 0x2ff
	s_cbranch_execz .LBB0_2159
	s_ashr_i32 s3, s2, 31
	s_ashr_i32 s4, s14, 5
	v_readlane_b32 s16, v250, 34
	s_ashr_i32 s5, s4, 31
	s_lshl_b64 s[8:9], s[2:3], 18
	v_readlane_b32 s22, v250, 40
	v_readlane_b32 s23, v250, 41
	s_add_u32 s3, s22, s8
	s_addc_u32 s8, s23, s9
	s_lshl_b64 s[4:5], s[4:5], 12
	s_add_u32 s4, s3, s4
	v_and_b32_e32 v0, 31, v2
	s_addc_u32 s5, s8, s5
	v_lshlrev_b32_e32 v3, 2, v0
	v_lshlrev_b32_e32 v4, 3, v2
	s_mov_b64 s[8:9], 0
	v_readlane_b32 s17, v250, 35
	v_readlane_b32 s18, v250, 36
	v_readlane_b32 s19, v250, 37
	v_readlane_b32 s20, v250, 38
	v_readlane_b32 s21, v250, 39
	v_readlane_b32 s24, v250, 42
	v_readlane_b32 s25, v250, 43
	v_readlane_b32 s26, v250, 44
	v_readlane_b32 s27, v250, 45
	v_readlane_b32 s28, v250, 46
	v_readlane_b32 s29, v250, 47
	v_readlane_b32 s30, v250, 48
	v_readlane_b32 s31, v250, 49
